# GEMM K-loops: in the second load segment of each K-tile the six LDS-DMA requests are issued before the eight ds_reads (slightly longer request look-ahead)
# speedup vs baseline: 1.0060x; 1.0060x over previous
; #define PG8_STAGE(bufoff, gbase, voff) do { _Pragma("unroll") for (int _i = 0; _i < 2; ++_i) \
;         __builtin_amdgcn_global_load_lds((const unsigned*)((const char*)(gbase) + (voff)[_i]), (PG8_LAS unsigned*)(lds + (bufoff) + ldsw + _i * 8192), 16, 0, 0); } while (0)
; #define PG8_LDA(dst, b, h) do { _Pragma("unroll") for (int m = 0; m < 4; ++m) _Pragma("unroll") for (int k = 0; k < 2; ++k) dst[m][k] = *(const PG8_LAS bf16x8*)(lds + PG8_SA(b, h) + aoff + m * 2048 + k * 1024); } while (0)
; #define PG8_LDB(dst, b, h) do { _Pragma("unroll") for (int n = 0; n < 2; ++n) _Pragma("unroll") for (int k = 0; k < 2; ++k) dst[n][k] = *(const PG8_LAS bf16x8*)(lds + PG8_SB(b, h) + boff + n * 2048 + k * 1024); } while (0)
; #define PG8_MMA(ai, bj, At, Bt) do { __builtin_amdgcn_s_setprio(1); _Pragma("unroll") for (int m = 0; m < 4; ++m) _Pragma("unroll") for (int n = 0; n < 2; ++n) _Pragma("unroll") for (int k = 0; k < 2; ++k) \
;         acc[ai][bj][m][n] = __builtin_amdgcn_mfma_f32_16x16x32_bf16(Bt[n][k], At[m][k], acc[ai][bj][m][n], 0, 0, 0); __builtin_amdgcn_s_setprio(0); } while (0)
; #define PG8_WAIT_V(n) asm volatile("s_waitcnt vmcnt(" #n ")" ::: "memory")
; #define PG8_BAR __builtin_amdgcn_s_barrier()
; template <class Epi, class Sched, bool ALIGN_EPI = false, bool SP2 = false>
; __device__ __forceinline__ void gemm_phase(PG8_LAS unsigned char* lds, const Gemm g, const Sched& S, const Epi& E) {
;     ...
;         for (int t = 0; t < nt; t += 2) {
;             const bool last = (t == nt - 2);
;             const char* a1 = cA + (size_t)(t + 1) * kstep;
;             const char* a2 = last ? nA : cA + (size_t)(t + 2) * kstep; const char* b2 = last ? nB : cB + (size_t)(t + 2) * kstep;
;             const char* a3 = a2 + kstep; const char* b3 = b2 + kstep;
;             if (last && has_next) S.a_ready(nxt);
;             if constexpr (SP2) {
;             PG8_LDB(B0, 0, 0); PG8_LDB(B1, 0, 1); PG8_SCHED; PG8_LDA(At, 0, 0); PG8_STAGE(PG8_SA(1, 1), a1 + hstep, voffA);
;             PG8_WAIT_V(8); PG8_WAIT_L(0); PG8_BAR; PG8_MMA(0, 0, At, B0); PG8_MMA(0, 1, At, B1); PG8_BAR; PG8_SCHED;
;             PG8_LDA(At, 0, 1); PG8_STAGE(PG8_SB(0, 0), b2, voffB); PG8_STAGE(PG8_SB(0, 1), b2 + hstep, voffB); PG8_STAGE(PG8_SA(0, 0), a2, voffA);
;             PG8_WAIT_V(8); PG8_WAIT_L(0); PG8_BAR; PG8_MMA(1, 0, At, B0); PG8_MMA(1, 1, At, B1); PG8_BAR; PG8_SCHED;
.LBB0_121:
	s_add_u32 s46, s44, 0xfffc0080
	s_addc_u32 s47, s45, -1
	s_add_i32 s64, 0, 0x10000
	s_cmp_eq_u32 s63, 12
	s_cselect_b32 s49, s41, s47
	s_cselect_b32 s48, s40, s46
	v_add_u32_e32 v146, s64, v149
	s_cselect_b32 s47, s37, s62
	s_cselect_b32 s46, s39, s61
	s_add_i32 s67, 0, 0x14000
	ds_read_b128 v[152:155], v146
	ds_read_b128 v[156:159], v146 offset:1024
	ds_read_b128 v[160:163], v146 offset:2048
	ds_read_b128 v[174:177], v146 offset:3072
	v_add_u32_e32 v146, s67, v149
	ds_read_b128 v[178:181], v146
	ds_read_b128 v[182:185], v146 offset:1024
	ds_read_b128 v[186:189], v146 offset:2048
	ds_read_b128 v[190:193], v146 offset:3072
	v_lshl_add_u64 v[146:147], s[44:45], 0, v[142:143]
	s_add_i32 m0, s52, 0xc000
	ds_read_b128 v[194:197], v151
	ds_read_b128 v[198:201], v151 offset:1024
	ds_read_b128 v[202:205], v151 offset:2048
	ds_read_b128 v[206:209], v151 offset:3072
	ds_read_b128 v[210:213], v151 offset:4096
	ds_read_b128 v[214:217], v151 offset:5120
	ds_read_b128 v[218:221], v151 offset:6144
	ds_read_b128 v[222:225], v151 offset:7168
	global_load_lds_dwordx4 v[146:147], off
	v_lshl_add_u64 v[146:147], s[44:45], 0, v[144:145]
	s_add_i32 m0, s52, 0xe000
	s_nop 0
	global_load_lds_dwordx4 v[146:147], off
	s_waitcnt vmcnt(8)
	s_waitcnt lgkmcnt(0)
	s_barrier
	s_setprio 1
	s_waitcnt lgkmcnt(0)
	v_mfma_f32_16x16x32_bf16 v[126:129], v[152:155], v[194:197], v[126:129]
	v_mfma_f32_16x16x32_bf16 v[122:125], v[160:163], v[194:197], v[122:125]
	v_mfma_f32_16x16x32_bf16 v[118:121], v[152:155], v[202:205], v[118:121]
	v_mfma_f32_16x16x32_bf16 v[110:113], v[160:163], v[202:205], v[110:113]
	v_mfma_f32_16x16x32_bf16 v[102:105], v[152:155], v[210:213], v[102:105]
	v_mfma_f32_16x16x32_bf16 v[94:97], v[160:163], v[210:213], v[94:97]
	v_mfma_f32_16x16x32_bf16 v[86:89], v[152:155], v[218:221], v[86:89]
	v_mfma_f32_16x16x32_bf16 v[78:81], v[160:163], v[218:221], v[78:81]
	v_mfma_f32_16x16x32_bf16 v[126:129], v[156:159], v[198:201], v[126:129]
	v_mfma_f32_16x16x32_bf16 v[122:125], v[174:177], v[198:201], v[122:125]
	v_mfma_f32_16x16x32_bf16 v[118:121], v[156:159], v[206:209], v[118:121]
	v_mfma_f32_16x16x32_bf16 v[110:113], v[174:177], v[206:209], v[110:113]
	v_mfma_f32_16x16x32_bf16 v[102:105], v[156:159], v[214:217], v[102:105]
	v_mfma_f32_16x16x32_bf16 v[94:97], v[174:177], v[214:217], v[94:97]
	v_mfma_f32_16x16x32_bf16 v[86:89], v[156:159], v[222:225], v[86:89]
	v_mfma_f32_16x16x32_bf16 v[78:81], v[174:177], v[222:225], v[78:81]
	s_setprio 0
	s_setprio 1
	v_mfma_f32_16x16x32_bf16 v[114:117], v[178:181], v[194:197], v[114:117]
	v_mfma_f32_16x16x32_bf16 v[106:109], v[186:189], v[194:197], v[106:109]
	v_mfma_f32_16x16x32_bf16 v[98:101], v[178:181], v[202:205], v[98:101]
	v_mfma_f32_16x16x32_bf16 v[90:93], v[186:189], v[202:205], v[90:93]
	v_mfma_f32_16x16x32_bf16 v[82:85], v[178:181], v[210:213], v[82:85]
	v_mfma_f32_16x16x32_bf16 v[74:77], v[186:189], v[210:213], v[74:77]
	v_mfma_f32_16x16x32_bf16 v[70:73], v[178:181], v[218:221], v[70:73]
	v_mfma_f32_16x16x32_bf16 v[66:69], v[186:189], v[218:221], v[66:69]
	v_mfma_f32_16x16x32_bf16 v[114:117], v[182:185], v[198:201], v[114:117]
	v_mfma_f32_16x16x32_bf16 v[106:109], v[190:193], v[198:201], v[106:109]
	v_mfma_f32_16x16x32_bf16 v[98:101], v[182:185], v[206:209], v[98:101]
	v_mfma_f32_16x16x32_bf16 v[90:93], v[190:193], v[206:209], v[90:93]
	v_mfma_f32_16x16x32_bf16 v[82:85], v[182:185], v[214:217], v[82:85]
	v_mfma_f32_16x16x32_bf16 v[74:77], v[190:193], v[214:217], v[74:77]
	v_mfma_f32_16x16x32_bf16 v[70:73], v[182:185], v[222:225], v[70:73]
	s_barrier
	v_mfma_f32_16x16x32_bf16 v[66:69], v[190:193], v[222:225], v[66:69]
	s_setprio 0
	s_add_i32 s64, s64, s34
	v_lshl_add_u64 v[146:147], s[46:47], 0, v[130:131]
	s_mov_b32 m0, s64
	s_nop 0
	global_load_lds_dwordx4 v[146:147], off
	s_add_i32 m0, s64, 0x2000
	s_add_u32 s64, s46, 0x40000
	v_lshl_add_u64 v[226:227], s[46:47], 0, v[136:137]
	s_addc_u32 s65, s47, 0
	s_add_i32 s67, s67, s34
	global_load_lds_dwordx4 v[226:227], off
	v_lshl_add_u64 v[228:229], s[64:65], 0, v[130:131]
	s_mov_b32 m0, s67
	v_lshl_add_u64 v[230:231], s[48:49], 0, v[138:139]
	global_load_lds_dwordx4 v[228:229], off
	v_lshl_add_u64 v[228:229], s[64:65], 0, v[136:137]
	s_add_i32 m0, s67, 0x2000
	s_nop 0
	global_load_lds_dwordx4 v[228:229], off
	v_lshl_add_u64 v[228:229], s[48:49], 0, v[140:141]
	s_mov_b32 m0, s52
	s_nop 0
	global_load_lds_dwordx4 v[228:229], off
	s_mov_b32 m0, s53
	s_nop 0
	global_load_lds_dwordx4 v[230:231], off
	ds_read_b128 v[194:197], v151 offset:16384
	ds_read_b128 v[198:201], v151 offset:17408
	ds_read_b128 v[202:205], v151 offset:18432
	ds_read_b128 v[206:209], v151 offset:19456
	ds_read_b128 v[210:213], v151 offset:20480
	ds_read_b128 v[214:217], v151 offset:21504
	ds_read_b128 v[218:221], v151 offset:22528
	ds_read_b128 v[222:225], v151 offset:23552
	s_waitcnt vmcnt(8)
	s_waitcnt lgkmcnt(0)
	s_barrier
; #define PG8_STAGE(bufoff, gbase, voff) do { _Pragma("unroll") for (int _i = 0; _i < 2; ++_i) \
;         __builtin_amdgcn_global_load_lds((const unsigned*)((const char*)(gbase) + (voff)[_i]), (PG8_LAS unsigned*)(lds + (bufoff) + ldsw + _i * 8192), 16, 0, 0); } while (0)
; #define PG8_LDA(dst, b, h) do { _Pragma("unroll") for (int m = 0; m < 4; ++m) _Pragma("unroll") for (int k = 0; k < 2; ++k) dst[m][k] = *(const PG8_LAS bf16x8*)(lds + PG8_SA(b, h) + aoff + m * 2048 + k * 1024); } while (0)
; #define PG8_LDB(dst, b, h) do { _Pragma("unroll") for (int n = 0; n < 2; ++n) _Pragma("unroll") for (int k = 0; k < 2; ++k) dst[n][k] = *(const PG8_LAS bf16x8*)(lds + PG8_SB(b, h) + boff + n * 2048 + k * 1024); } while (0)
; #define PG8_MMA(ai, bj, At, Bt) do { __builtin_amdgcn_s_setprio(1); _Pragma("unroll") for (int m = 0; m < 4; ++m) _Pragma("unroll") for (int n = 0; n < 2; ++n) _Pragma("unroll") for (int k = 0; k < 2; ++k) \
;         acc[ai][bj][m][n] = __builtin_amdgcn_mfma_f32_16x16x32_bf16(Bt[n][k], At[m][k], acc[ai][bj][m][n], 0, 0, 0); __builtin_amdgcn_s_setprio(0); } while (0)
; #define PG8_WAIT_V(n) asm volatile("s_waitcnt vmcnt(" #n ")" ::: "memory")
; #define PG8_WAIT_L(n) asm volatile("s_waitcnt lgkmcnt(" #n ")" ::: "memory")
; #define PG8_BAR __builtin_amdgcn_s_barrier()
; #define PG8_SCHED __builtin_amdgcn_sched_barrier(0)
; template <class Epi, class Sched, bool ALIGN_EPI = false, bool SP2 = false>
; __device__ __forceinline__ void gemm_phase(PG8_LAS unsigned char* lds, const Gemm g, const Sched& S, const Epi& E) {
;     ...
;             PG8_WAIT_V(8); PG8_WAIT_L(0); PG8_BAR; PG8_MMA(1, 0, At, B0); PG8_MMA(1, 1, At, B1); PG8_BAR; PG8_SCHED;
;             PG8_LDB(B0, 1, 0); PG8_LDB(B1, 1, 1); PG8_SCHED; PG8_LDA(At, 1, 0); PG8_STAGE(PG8_SA(0, 1), a2 + hstep, voffA);
;             PG8_WAIT_V(8); PG8_WAIT_L(0); PG8_BAR; PG8_MMA(0, 0, At, B0); PG8_MMA(0, 1, At, B1); PG8_BAR; PG8_SCHED;
	s_setprio 1
	s_waitcnt lgkmcnt(0)
	v_mfma_f32_16x16x32_bf16 v[62:65], v[152:155], v[194:197], v[62:65]
	v_mfma_f32_16x16x32_bf16 v[58:61], v[160:163], v[194:197], v[58:61]
	v_mfma_f32_16x16x32_bf16 v[54:57], v[152:155], v[202:205], v[54:57]
	v_mfma_f32_16x16x32_bf16 v[46:49], v[160:163], v[202:205], v[46:49]
	v_mfma_f32_16x16x32_bf16 v[38:41], v[152:155], v[210:213], v[38:41]
	v_mfma_f32_16x16x32_bf16 v[30:33], v[160:163], v[210:213], v[30:33]
	v_mfma_f32_16x16x32_bf16 v[22:25], v[152:155], v[218:221], v[22:25]
	v_mfma_f32_16x16x32_bf16 v[14:17], v[160:163], v[218:221], v[14:17]
	v_mfma_f32_16x16x32_bf16 v[62:65], v[156:159], v[198:201], v[62:65]
	v_mfma_f32_16x16x32_bf16 v[58:61], v[174:177], v[198:201], v[58:61]
	v_mfma_f32_16x16x32_bf16 v[54:57], v[156:159], v[206:209], v[54:57]
	v_mfma_f32_16x16x32_bf16 v[46:49], v[174:177], v[206:209], v[46:49]
	v_mfma_f32_16x16x32_bf16 v[38:41], v[156:159], v[214:217], v[38:41]
	v_mfma_f32_16x16x32_bf16 v[30:33], v[174:177], v[214:217], v[30:33]
	v_mfma_f32_16x16x32_bf16 v[22:25], v[156:159], v[222:225], v[22:25]
	v_mfma_f32_16x16x32_bf16 v[14:17], v[174:177], v[222:225], v[14:17]
	s_setprio 0
	s_setprio 1
	v_mfma_f32_16x16x32_bf16 v[50:53], v[178:181], v[194:197], v[50:53]
	v_mfma_f32_16x16x32_bf16 v[42:45], v[186:189], v[194:197], v[42:45]
	v_mfma_f32_16x16x32_bf16 v[34:37], v[178:181], v[202:205], v[34:37]
	v_mfma_f32_16x16x32_bf16 v[26:29], v[186:189], v[202:205], v[26:29]
	v_mfma_f32_16x16x32_bf16 v[18:21], v[178:181], v[210:213], v[18:21]
	v_mfma_f32_16x16x32_bf16 v[10:13], v[186:189], v[210:213], v[10:13]
	v_mfma_f32_16x16x32_bf16 v[6:9], v[178:181], v[218:221], v[6:9]
	v_mfma_f32_16x16x32_bf16 v[2:5], v[186:189], v[218:221], v[2:5]
	v_mfma_f32_16x16x32_bf16 v[50:53], v[182:185], v[198:201], v[50:53]
	v_mfma_f32_16x16x32_bf16 v[42:45], v[190:193], v[198:201], v[42:45]
	v_mfma_f32_16x16x32_bf16 v[34:37], v[182:185], v[206:209], v[34:37]
	v_mfma_f32_16x16x32_bf16 v[26:29], v[190:193], v[206:209], v[26:29]
	v_mfma_f32_16x16x32_bf16 v[18:21], v[182:185], v[214:217], v[18:21]
	v_mfma_f32_16x16x32_bf16 v[10:13], v[190:193], v[214:217], v[10:13]
	v_mfma_f32_16x16x32_bf16 v[6:9], v[182:185], v[222:225], v[6:9]
	s_barrier
	v_mfma_f32_16x16x32_bf16 v[2:5], v[190:193], v[222:225], v[2:5]
	s_setprio 0
	s_add_i32 s64, 0, 0x18000
	v_add_u32_e32 v173, s64, v149
	s_add_i32 s65, 0, 0x1c000
	ds_read_b128 v[152:155], v173
	ds_read_b128 v[156:159], v173 offset:1024
	ds_read_b128 v[160:163], v173 offset:2048
	ds_read_b128 v[174:177], v173 offset:3072
	v_add_u32_e32 v173, s65, v149
	ds_read_b128 v[178:181], v173
	ds_read_b128 v[182:185], v173 offset:1024
	ds_read_b128 v[186:189], v173 offset:2048
	ds_read_b128 v[190:193], v173 offset:3072
	s_add_u32 s48, s48, 0x40000
	s_addc_u32 s49, s49, 0
	s_mov_b32 m0, s54
	v_lshl_add_u64 v[232:233], s[48:49], 0, v[140:141]
	ds_read_b128 v[194:197], v151 offset:32768
	ds_read_b128 v[198:201], v151 offset:33792
	ds_read_b128 v[202:205], v151 offset:34816
	ds_read_b128 v[206:209], v151 offset:35840
	ds_read_b128 v[210:213], v151 offset:36864
	ds_read_b128 v[214:217], v151 offset:37888
	ds_read_b128 v[218:221], v151 offset:38912
	ds_read_b128 v[222:225], v151 offset:39936
	global_load_lds_dwordx4 v[232:233], off
	v_lshl_add_u64 v[232:233], s[48:49], 0, v[138:139]
	s_mov_b32 m0, s55
	s_nop 0
	global_load_lds_dwordx4 v[232:233], off
	s_waitcnt vmcnt(8)
	s_waitcnt lgkmcnt(0)
	s_barrier
	s_setprio 1
	s_waitcnt lgkmcnt(0)
	v_mfma_f32_16x16x32_bf16 v[126:129], v[152:155], v[194:197], v[126:129]
	v_mfma_f32_16x16x32_bf16 v[122:125], v[160:163], v[194:197], v[122:125]
	v_mfma_f32_16x16x32_bf16 v[118:121], v[152:155], v[202:205], v[118:121]
	v_mfma_f32_16x16x32_bf16 v[110:113], v[160:163], v[202:205], v[110:113]
	v_mfma_f32_16x16x32_bf16 v[102:105], v[152:155], v[210:213], v[102:105]
	v_mfma_f32_16x16x32_bf16 v[94:97], v[160:163], v[210:213], v[94:97]
	v_mfma_f32_16x16x32_bf16 v[86:89], v[152:155], v[218:221], v[86:89]
	v_mfma_f32_16x16x32_bf16 v[78:81], v[160:163], v[218:221], v[78:81]
	v_mfma_f32_16x16x32_bf16 v[126:129], v[156:159], v[198:201], v[126:129]
	v_mfma_f32_16x16x32_bf16 v[122:125], v[174:177], v[198:201], v[122:125]
	v_mfma_f32_16x16x32_bf16 v[118:121], v[156:159], v[206:209], v[118:121]
	v_mfma_f32_16x16x32_bf16 v[110:113], v[174:177], v[206:209], v[110:113]
	v_mfma_f32_16x16x32_bf16 v[102:105], v[156:159], v[214:217], v[102:105]
	v_mfma_f32_16x16x32_bf16 v[94:97], v[174:177], v[214:217], v[94:97]
	v_mfma_f32_16x16x32_bf16 v[86:89], v[156:159], v[222:225], v[86:89]
	v_mfma_f32_16x16x32_bf16 v[78:81], v[174:177], v[222:225], v[78:81]
	s_setprio 0
	s_setprio 1
	v_mfma_f32_16x16x32_bf16 v[114:117], v[178:181], v[194:197], v[114:117]
	v_mfma_f32_16x16x32_bf16 v[106:109], v[186:189], v[194:197], v[106:109]
	v_mfma_f32_16x16x32_bf16 v[98:101], v[178:181], v[202:205], v[98:101]
	v_mfma_f32_16x16x32_bf16 v[90:93], v[186:189], v[202:205], v[90:93]
	v_mfma_f32_16x16x32_bf16 v[82:85], v[178:181], v[210:213], v[82:85]
	v_mfma_f32_16x16x32_bf16 v[74:77], v[186:189], v[210:213], v[74:77]
	v_mfma_f32_16x16x32_bf16 v[70:73], v[178:181], v[218:221], v[70:73]
	v_mfma_f32_16x16x32_bf16 v[66:69], v[186:189], v[218:221], v[66:69]
	v_mfma_f32_16x16x32_bf16 v[114:117], v[182:185], v[198:201], v[114:117]
	v_mfma_f32_16x16x32_bf16 v[106:109], v[190:193], v[198:201], v[106:109]
	v_mfma_f32_16x16x32_bf16 v[98:101], v[182:185], v[206:209], v[98:101]
	v_mfma_f32_16x16x32_bf16 v[90:93], v[190:193], v[206:209], v[90:93]
	v_mfma_f32_16x16x32_bf16 v[82:85], v[182:185], v[214:217], v[82:85]
	v_mfma_f32_16x16x32_bf16 v[74:77], v[190:193], v[214:217], v[74:77]
	v_mfma_f32_16x16x32_bf16 v[70:73], v[182:185], v[222:225], v[70:73]
	s_barrier
; #define PG8_STAGE(bufoff, gbase, voff) do { _Pragma("unroll") for (int _i = 0; _i < 2; ++_i) \
;         __builtin_amdgcn_global_load_lds((const unsigned*)((const char*)(gbase) + (voff)[_i]), (PG8_LAS unsigned*)(lds + (bufoff) + ldsw + _i * 8192), 16, 0, 0); } while (0)
; #define PG8_LDA(dst, b, h) do { _Pragma("unroll") for (int m = 0; m < 4; ++m) _Pragma("unroll") for (int k = 0; k < 2; ++k) dst[m][k] = *(const PG8_LAS bf16x8*)(lds + PG8_SA(b, h) + aoff + m * 2048 + k * 1024); } while (0)
; #define PG8_MMA(ai, bj, At, Bt) do { __builtin_amdgcn_s_setprio(1); _Pragma("unroll") for (int m = 0; m < 4; ++m) _Pragma("unroll") for (int n = 0; n < 2; ++n) _Pragma("unroll") for (int k = 0; k < 2; ++k) \
;         acc[ai][bj][m][n] = __builtin_amdgcn_mfma_f32_16x16x32_bf16(Bt[n][k], At[m][k], acc[ai][bj][m][n], 0, 0, 0); __builtin_amdgcn_s_setprio(0); } while (0)
; #define PG8_WAIT_V(n) asm volatile("s_waitcnt vmcnt(" #n ")" ::: "memory")
; #define PG8_WAIT_L(n) asm volatile("s_waitcnt lgkmcnt(" #n ")" ::: "memory")
; #define PG8_BAR __builtin_amdgcn_s_barrier()
; #define PG8_SCHED __builtin_amdgcn_sched_barrier(0)
; template <class Epi, class Sched, bool ALIGN_EPI = false, bool SP2 = false>
; __device__ __forceinline__ void gemm_phase(PG8_LAS unsigned char* lds, const Gemm g, const Sched& S, const Epi& E) {
;     ...
;         for (int t = 0; t < nt; t += 2) {
;             const bool last = (t == nt - 2);
;             const char* a1 = cA + (size_t)(t + 1) * kstep;
;             const char* a2 = last ? nA : cA + (size_t)(t + 2) * kstep; const char* b2 = last ? nB : cB + (size_t)(t + 2) * kstep;
;             const char* a3 = a2 + kstep; const char* b3 = b2 + kstep;
;     ...
;             PG8_WAIT_V(8); PG8_WAIT_L(0); PG8_BAR; PG8_MMA(0, 0, At, B0); PG8_MMA(0, 1, At, B1); PG8_BAR; PG8_SCHED;
;             PG8_LDA(At, 1, 1); PG8_STAGE(PG8_SB(1, 0), b3, voffB); PG8_STAGE(PG8_SB(1, 1), b3 + hstep, voffB); PG8_STAGE(PG8_SA(1, 0), a3, voffA);
;             PG8_WAIT_V(8); PG8_WAIT_L(0); PG8_BAR; PG8_MMA(1, 0, At, B0); PG8_MMA(1, 1, At, B1); PG8_BAR; PG8_SCHED;
	v_mfma_f32_16x16x32_bf16 v[66:69], v[190:193], v[222:225], v[66:69]
	s_setprio 0
	s_add_i32 s48, s64, s34
	v_lshl_add_u64 v[146:147], v[146:147], 0, s[96:97]
	s_mov_b32 m0, s48
	s_nop 0
	global_load_lds_dwordx4 v[146:147], off
	s_add_i32 m0, s48, 0x2000
	s_add_u32 s46, s46, 0x40080
	v_lshl_add_u64 v[146:147], v[226:227], 0, s[96:97]
	s_addc_u32 s47, s47, 0
	s_add_i32 s48, s65, s34
	global_load_lds_dwordx4 v[146:147], off
	v_lshl_add_u64 v[146:147], s[46:47], 0, v[130:131]
	s_mov_b32 m0, s48
	s_nop 0
	global_load_lds_dwordx4 v[146:147], off
	v_lshl_add_u64 v[146:147], s[46:47], 0, v[136:137]
	s_add_i32 m0, s48, 0x2000
	s_nop 0
	global_load_lds_dwordx4 v[146:147], off
	v_lshl_add_u64 v[146:147], v[228:229], 0, s[96:97]
	s_mov_b32 m0, s56
	s_nop 0
	global_load_lds_dwordx4 v[146:147], off
	v_lshl_add_u64 v[146:147], v[230:231], 0, s[96:97]
	s_mov_b32 m0, s57
	s_nop 0
	global_load_lds_dwordx4 v[146:147], off
	ds_read_b128 v[194:197], v151 offset:49152
	ds_read_b128 v[198:201], v151 offset:50176
	ds_read_b128 v[202:205], v151 offset:51200
	ds_read_b128 v[206:209], v151 offset:52224
	ds_read_b128 v[210:213], v151 offset:53248
	ds_read_b128 v[214:217], v151 offset:54272
	ds_read_b128 v[218:221], v151 offset:55296
	ds_read_b128 v[222:225], v151 offset:56320
	s_waitcnt vmcnt(8)
	s_waitcnt lgkmcnt(0)
	s_barrier
	s_setprio 1
	s_waitcnt lgkmcnt(0)
	v_mfma_f32_16x16x32_bf16 v[62:65], v[152:155], v[194:197], v[62:65]
	v_mfma_f32_16x16x32_bf16 v[58:61], v[160:163], v[194:197], v[58:61]
	v_mfma_f32_16x16x32_bf16 v[54:57], v[152:155], v[202:205], v[54:57]
	v_mfma_f32_16x16x32_bf16 v[46:49], v[160:163], v[202:205], v[46:49]
	v_mfma_f32_16x16x32_bf16 v[38:41], v[152:155], v[210:213], v[38:41]
	v_mfma_f32_16x16x32_bf16 v[30:33], v[160:163], v[210:213], v[30:33]
	v_mfma_f32_16x16x32_bf16 v[22:25], v[152:155], v[218:221], v[22:25]
	v_mfma_f32_16x16x32_bf16 v[14:17], v[160:163], v[218:221], v[14:17]
	v_mfma_f32_16x16x32_bf16 v[62:65], v[156:159], v[198:201], v[62:65]
	v_mfma_f32_16x16x32_bf16 v[58:61], v[174:177], v[198:201], v[58:61]
	v_mfma_f32_16x16x32_bf16 v[54:57], v[156:159], v[206:209], v[54:57]
	v_mfma_f32_16x16x32_bf16 v[46:49], v[174:177], v[206:209], v[46:49]
	v_mfma_f32_16x16x32_bf16 v[38:41], v[156:159], v[214:217], v[38:41]
	v_mfma_f32_16x16x32_bf16 v[30:33], v[174:177], v[214:217], v[30:33]
	v_mfma_f32_16x16x32_bf16 v[22:25], v[156:159], v[222:225], v[22:25]
	v_mfma_f32_16x16x32_bf16 v[14:17], v[174:177], v[222:225], v[14:17]
	s_setprio 0
	s_setprio 1
	v_mfma_f32_16x16x32_bf16 v[50:53], v[178:181], v[194:197], v[50:53]
	v_mfma_f32_16x16x32_bf16 v[42:45], v[186:189], v[194:197], v[42:45]
	v_mfma_f32_16x16x32_bf16 v[34:37], v[178:181], v[202:205], v[34:37]
	v_mfma_f32_16x16x32_bf16 v[26:29], v[186:189], v[202:205], v[26:29]
	v_mfma_f32_16x16x32_bf16 v[18:21], v[178:181], v[210:213], v[18:21]
	v_mfma_f32_16x16x32_bf16 v[10:13], v[186:189], v[210:213], v[10:13]
	v_mfma_f32_16x16x32_bf16 v[6:9], v[178:181], v[218:221], v[6:9]
	v_mfma_f32_16x16x32_bf16 v[2:5], v[186:189], v[218:221], v[2:5]
	v_mfma_f32_16x16x32_bf16 v[50:53], v[182:185], v[198:201], v[50:53]
	v_mfma_f32_16x16x32_bf16 v[42:45], v[190:193], v[198:201], v[42:45]
	v_mfma_f32_16x16x32_bf16 v[34:37], v[182:185], v[206:209], v[34:37]
	v_mfma_f32_16x16x32_bf16 v[26:29], v[190:193], v[206:209], v[26:29]
	v_mfma_f32_16x16x32_bf16 v[18:21], v[182:185], v[214:217], v[18:21]
	v_mfma_f32_16x16x32_bf16 v[10:13], v[190:193], v[214:217], v[10:13]
	v_mfma_f32_16x16x32_bf16 v[6:9], v[182:185], v[222:225], v[6:9]
	s_barrier
	v_mfma_f32_16x16x32_bf16 v[2:5], v[190:193], v[222:225], v[2:5]
	s_setprio 0
	s_add_i32 s63, s63, 2
	s_add_u32 s44, s44, 0x100
	s_addc_u32 s45, s45, 0
	s_add_u32 s61, s61, 0x100
	s_addc_u32 s62, s62, 0
	s_cmp_gt_u32 s63, 13
	s_cbranch_scc0 .LBB0_121
	s_and_b64 vcc, exec, s[6:7]
	s_cbranch_vccz .LBB0_124
	s_barrier

; #define PG8_STAGE(bufoff, gbase, voff) do { _Pragma("unroll") for (int _i = 0; _i < 2; ++_i) \
;         __builtin_amdgcn_global_load_lds((const unsigned*)((const char*)(gbase) + (voff)[_i]), (PG8_LAS unsigned*)(lds + (bufoff) + ldsw + _i * 8192), 16, 0, 0); } while (0)
; #define PG8_LDA(dst, b, h) do { _Pragma("unroll") for (int m = 0; m < 4; ++m) _Pragma("unroll") for (int k = 0; k < 2; ++k) dst[m][k] = *(const PG8_LAS bf16x8*)(lds + PG8_SA(b, h) + aoff + m * 2048 + k * 1024); } while (0)
; #define PG8_LDB(dst, b, h) do { _Pragma("unroll") for (int n = 0; n < 2; ++n) _Pragma("unroll") for (int k = 0; k < 2; ++k) dst[n][k] = *(const PG8_LAS bf16x8*)(lds + PG8_SB(b, h) + boff + n * 2048 + k * 1024); } while (0)
; #define PG8_MMA(ai, bj, At, Bt) do { __builtin_amdgcn_s_setprio(1); _Pragma("unroll") for (int m = 0; m < 4; ++m) _Pragma("unroll") for (int n = 0; n < 2; ++n) _Pragma("unroll") for (int k = 0; k < 2; ++k) \
;         acc[ai][bj][m][n] = __builtin_amdgcn_mfma_f32_16x16x32_bf16(Bt[n][k], At[m][k], acc[ai][bj][m][n], 0, 0, 0); __builtin_amdgcn_s_setprio(0); } while (0)
; #define PG8_WAIT_V(n) asm volatile("s_waitcnt vmcnt(" #n ")" ::: "memory")
; #define PG8_BAR __builtin_amdgcn_s_barrier()
; template <class Epi, class Sched, bool ALIGN_EPI = false, bool SP2 = false>
; __device__ __forceinline__ void gemm_phase(PG8_LAS unsigned char* lds, const Gemm g, const Sched& S, const Epi& E) {
;     ...
;         for (int t = 0; t < nt; t += 2) {
;             const bool last = (t == nt - 2);
;             const char* a1 = cA + (size_t)(t + 1) * kstep;
;             const char* a2 = last ? nA : cA + (size_t)(t + 2) * kstep; const char* b2 = last ? nB : cB + (size_t)(t + 2) * kstep;
;             const char* a3 = a2 + kstep; const char* b3 = b2 + kstep;
;             if (last && has_next) S.a_ready(nxt);
;             if constexpr (SP2) {
;             PG8_LDB(B0, 0, 0); PG8_LDB(B1, 0, 1); PG8_SCHED; PG8_LDA(At, 0, 0); PG8_STAGE(PG8_SA(1, 1), a1 + hstep, voffA);
;             PG8_WAIT_V(8); PG8_WAIT_L(0); PG8_BAR; PG8_MMA(0, 0, At, B0); PG8_MMA(0, 1, At, B1); PG8_BAR; PG8_SCHED;
;             PG8_LDA(At, 0, 1); PG8_STAGE(PG8_SB(0, 0), b2, voffB); PG8_STAGE(PG8_SB(0, 1), b2 + hstep, voffB); PG8_STAGE(PG8_SA(0, 0), a2, voffA);
;             PG8_WAIT_V(8); PG8_WAIT_L(0); PG8_BAR; PG8_MMA(1, 0, At, B0); PG8_MMA(1, 1, At, B1); PG8_BAR; PG8_SCHED;
.LBB0_811:
	ds_read_b128 v[130:133], v159
	ds_read_b128 v[152:155], v159 offset:1024
	ds_read_b128 v[166:169], v159 offset:2048
	ds_read_b128 v[170:173], v159 offset:3072
	ds_read_b128 v[174:177], v160
	ds_read_b128 v[178:181], v160 offset:1024
	ds_read_b128 v[182:185], v160 offset:2048
	ds_read_b128 v[186:189], v160 offset:3072
	s_add_u32 s42, s4, 0xfffc0080
	s_addc_u32 s43, s5, -1
	s_cmp_eq_u32 s47, 12
	s_cselect_b32 s45, s35, s43
	s_cselect_b32 s44, s34, s42
	s_cselect_b32 s43, s6, s46
	s_cselect_b32 s42, s23, s25
	v_lshl_add_u64 v[162:163], s[4:5], 0, v[144:145]
	s_add_i32 m0, s39, 0xc000
	ds_read_b128 v[190:193], v161
	ds_read_b128 v[194:197], v161 offset:1024
	ds_read_b128 v[198:201], v161 offset:2048
	ds_read_b128 v[202:205], v161 offset:3072
	ds_read_b128 v[206:209], v161 offset:4096
	ds_read_b128 v[210:213], v161 offset:5120
	ds_read_b128 v[214:217], v161 offset:6144
	ds_read_b128 v[218:221], v161 offset:7168
	global_load_lds_dwordx4 v[162:163], off
	v_lshl_add_u64 v[162:163], s[4:5], 0, v[146:147]
	s_add_i32 m0, s39, 0xe000
	s_nop 0
	global_load_lds_dwordx4 v[162:163], off
	s_waitcnt vmcnt(8)
	s_waitcnt lgkmcnt(0)
	s_barrier
	s_setprio 1
	s_waitcnt lgkmcnt(0)
	v_mfma_f32_16x16x32_bf16 v[126:129], v[130:133], v[190:193], v[126:129]
	v_mfma_f32_16x16x32_bf16 v[122:125], v[166:169], v[190:193], v[122:125]
	v_mfma_f32_16x16x32_bf16 v[110:113], v[130:133], v[198:201], v[110:113]
	v_mfma_f32_16x16x32_bf16 v[106:109], v[166:169], v[198:201], v[106:109]
	v_mfma_f32_16x16x32_bf16 v[94:97], v[130:133], v[206:209], v[94:97]
	v_mfma_f32_16x16x32_bf16 v[90:93], v[166:169], v[206:209], v[90:93]
	v_mfma_f32_16x16x32_bf16 v[78:81], v[130:133], v[214:217], v[78:81]
	v_mfma_f32_16x16x32_bf16 v[74:77], v[166:169], v[214:217], v[74:77]
	v_mfma_f32_16x16x32_bf16 v[126:129], v[152:155], v[194:197], v[126:129]
	v_mfma_f32_16x16x32_bf16 v[122:125], v[170:173], v[194:197], v[122:125]
	v_mfma_f32_16x16x32_bf16 v[110:113], v[152:155], v[202:205], v[110:113]
	v_mfma_f32_16x16x32_bf16 v[106:109], v[170:173], v[202:205], v[106:109]
	v_mfma_f32_16x16x32_bf16 v[94:97], v[152:155], v[210:213], v[94:97]
	v_mfma_f32_16x16x32_bf16 v[90:93], v[170:173], v[210:213], v[90:93]
	v_mfma_f32_16x16x32_bf16 v[78:81], v[152:155], v[218:221], v[78:81]
	v_mfma_f32_16x16x32_bf16 v[74:77], v[170:173], v[218:221], v[74:77]
	s_setprio 0
	s_setprio 1
	v_mfma_f32_16x16x32_bf16 v[118:121], v[174:177], v[190:193], v[118:121]
	v_mfma_f32_16x16x32_bf16 v[114:117], v[182:185], v[190:193], v[114:117]
	v_mfma_f32_16x16x32_bf16 v[102:105], v[174:177], v[198:201], v[102:105]
	v_mfma_f32_16x16x32_bf16 v[98:101], v[182:185], v[198:201], v[98:101]
	v_mfma_f32_16x16x32_bf16 v[86:89], v[174:177], v[206:209], v[86:89]
	v_mfma_f32_16x16x32_bf16 v[82:85], v[182:185], v[206:209], v[82:85]
	v_mfma_f32_16x16x32_bf16 v[70:73], v[174:177], v[214:217], v[70:73]
	v_mfma_f32_16x16x32_bf16 v[66:69], v[182:185], v[214:217], v[66:69]
	v_mfma_f32_16x16x32_bf16 v[118:121], v[178:181], v[194:197], v[118:121]
	v_mfma_f32_16x16x32_bf16 v[114:117], v[186:189], v[194:197], v[114:117]
	v_mfma_f32_16x16x32_bf16 v[102:105], v[178:181], v[202:205], v[102:105]
	v_mfma_f32_16x16x32_bf16 v[98:101], v[186:189], v[202:205], v[98:101]
	v_mfma_f32_16x16x32_bf16 v[86:89], v[178:181], v[210:213], v[86:89]
	v_mfma_f32_16x16x32_bf16 v[82:85], v[186:189], v[210:213], v[82:85]
	v_mfma_f32_16x16x32_bf16 v[70:73], v[178:181], v[218:221], v[70:73]
	s_barrier
	v_mfma_f32_16x16x32_bf16 v[66:69], v[186:189], v[218:221], v[66:69]
	s_setprio 0
	s_add_i32 s61, s54, s33
	v_lshl_add_u64 v[162:163], s[42:43], 0, v[136:137]
	s_mov_b32 m0, s61
	s_nop 0
	global_load_lds_dwordx4 v[162:163], off
	s_add_i32 m0, s61, 0x2000
	s_add_u32 s62, s42, 0x40000
	v_lshl_add_u64 v[222:223], s[42:43], 0, v[140:141]
	s_addc_u32 s63, s43, 0
	s_add_i32 s61, s55, s33
	global_load_lds_dwordx4 v[222:223], off
	v_lshl_add_u64 v[224:225], s[62:63], 0, v[136:137]
	s_mov_b32 m0, s61
	v_lshl_add_u64 v[226:227], s[44:45], 0, v[138:139]
	global_load_lds_dwordx4 v[224:225], off
	v_lshl_add_u64 v[224:225], s[62:63], 0, v[140:141]
	s_add_i32 m0, s61, 0x2000
	s_nop 0
	global_load_lds_dwordx4 v[224:225], off
	v_lshl_add_u64 v[224:225], s[44:45], 0, v[134:135]
	s_mov_b32 m0, s39
	s_nop 0
	global_load_lds_dwordx4 v[224:225], off
	s_mov_b32 m0, s49
	s_nop 0
	global_load_lds_dwordx4 v[226:227], off
	ds_read_b128 v[190:193], v161 offset:16384
	ds_read_b128 v[194:197], v161 offset:17408
	ds_read_b128 v[198:201], v161 offset:18432
	ds_read_b128 v[202:205], v161 offset:19456
	ds_read_b128 v[206:209], v161 offset:20480
	ds_read_b128 v[210:213], v161 offset:21504
	ds_read_b128 v[214:217], v161 offset:22528
	ds_read_b128 v[218:221], v161 offset:23552
	s_waitcnt vmcnt(8)
	s_waitcnt lgkmcnt(0)
	s_barrier
; #define PG8_STAGE(bufoff, gbase, voff) do { _Pragma("unroll") for (int _i = 0; _i < 2; ++_i) \
;         __builtin_amdgcn_global_load_lds((const unsigned*)((const char*)(gbase) + (voff)[_i]), (PG8_LAS unsigned*)(lds + (bufoff) + ldsw + _i * 8192), 16, 0, 0); } while (0)
; #define PG8_LDA(dst, b, h) do { _Pragma("unroll") for (int m = 0; m < 4; ++m) _Pragma("unroll") for (int k = 0; k < 2; ++k) dst[m][k] = *(const PG8_LAS bf16x8*)(lds + PG8_SA(b, h) + aoff + m * 2048 + k * 1024); } while (0)
; #define PG8_LDB(dst, b, h) do { _Pragma("unroll") for (int n = 0; n < 2; ++n) _Pragma("unroll") for (int k = 0; k < 2; ++k) dst[n][k] = *(const PG8_LAS bf16x8*)(lds + PG8_SB(b, h) + boff + n * 2048 + k * 1024); } while (0)
; #define PG8_MMA(ai, bj, At, Bt) do { __builtin_amdgcn_s_setprio(1); _Pragma("unroll") for (int m = 0; m < 4; ++m) _Pragma("unroll") for (int n = 0; n < 2; ++n) _Pragma("unroll") for (int k = 0; k < 2; ++k) \
;         acc[ai][bj][m][n] = __builtin_amdgcn_mfma_f32_16x16x32_bf16(Bt[n][k], At[m][k], acc[ai][bj][m][n], 0, 0, 0); __builtin_amdgcn_s_setprio(0); } while (0)
; #define PG8_WAIT_V(n) asm volatile("s_waitcnt vmcnt(" #n ")" ::: "memory")
; #define PG8_WAIT_L(n) asm volatile("s_waitcnt lgkmcnt(" #n ")" ::: "memory")
; #define PG8_BAR __builtin_amdgcn_s_barrier()
; #define PG8_SCHED __builtin_amdgcn_sched_barrier(0)
; template <class Epi, class Sched, bool ALIGN_EPI = false, bool SP2 = false>
; __device__ __forceinline__ void gemm_phase(PG8_LAS unsigned char* lds, const Gemm g, const Sched& S, const Epi& E) {
;     ...
;             PG8_WAIT_V(8); PG8_WAIT_L(0); PG8_BAR; PG8_MMA(1, 0, At, B0); PG8_MMA(1, 1, At, B1); PG8_BAR; PG8_SCHED;
;             PG8_LDB(B0, 1, 0); PG8_LDB(B1, 1, 1); PG8_SCHED; PG8_LDA(At, 1, 0); PG8_STAGE(PG8_SA(0, 1), a2 + hstep, voffA);
;             PG8_WAIT_V(8); PG8_WAIT_L(0); PG8_BAR; PG8_MMA(0, 0, At, B0); PG8_MMA(0, 1, At, B1); PG8_BAR; PG8_SCHED;
	s_setprio 1
	s_waitcnt lgkmcnt(0)
	v_mfma_f32_16x16x32_bf16 v[62:65], v[130:133], v[190:193], v[62:65]
	v_mfma_f32_16x16x32_bf16 v[58:61], v[166:169], v[190:193], v[58:61]
	v_mfma_f32_16x16x32_bf16 v[46:49], v[130:133], v[198:201], v[46:49]
	v_mfma_f32_16x16x32_bf16 v[42:45], v[166:169], v[198:201], v[42:45]
	v_mfma_f32_16x16x32_bf16 v[30:33], v[130:133], v[206:209], v[30:33]
	v_mfma_f32_16x16x32_bf16 v[26:29], v[166:169], v[206:209], v[26:29]
	v_mfma_f32_16x16x32_bf16 v[14:17], v[130:133], v[214:217], v[14:17]
	v_mfma_f32_16x16x32_bf16 v[10:13], v[166:169], v[214:217], v[10:13]
	v_mfma_f32_16x16x32_bf16 v[62:65], v[152:155], v[194:197], v[62:65]
	v_mfma_f32_16x16x32_bf16 v[58:61], v[170:173], v[194:197], v[58:61]
	v_mfma_f32_16x16x32_bf16 v[46:49], v[152:155], v[202:205], v[46:49]
	v_mfma_f32_16x16x32_bf16 v[42:45], v[170:173], v[202:205], v[42:45]
	v_mfma_f32_16x16x32_bf16 v[30:33], v[152:155], v[210:213], v[30:33]
	v_mfma_f32_16x16x32_bf16 v[26:29], v[170:173], v[210:213], v[26:29]
	v_mfma_f32_16x16x32_bf16 v[14:17], v[152:155], v[218:221], v[14:17]
	v_mfma_f32_16x16x32_bf16 v[10:13], v[170:173], v[218:221], v[10:13]
	s_setprio 0
	s_setprio 1
	v_mfma_f32_16x16x32_bf16 v[54:57], v[174:177], v[190:193], v[54:57]
	v_mfma_f32_16x16x32_bf16 v[50:53], v[182:185], v[190:193], v[50:53]
	v_mfma_f32_16x16x32_bf16 v[38:41], v[174:177], v[198:201], v[38:41]
	v_mfma_f32_16x16x32_bf16 v[34:37], v[182:185], v[198:201], v[34:37]
	v_mfma_f32_16x16x32_bf16 v[22:25], v[174:177], v[206:209], v[22:25]
	v_mfma_f32_16x16x32_bf16 v[18:21], v[182:185], v[206:209], v[18:21]
	v_mfma_f32_16x16x32_bf16 v[6:9], v[174:177], v[214:217], v[6:9]
	v_mfma_f32_16x16x32_bf16 v[2:5], v[182:185], v[214:217], v[2:5]
	v_mfma_f32_16x16x32_bf16 v[54:57], v[178:181], v[194:197], v[54:57]
	v_mfma_f32_16x16x32_bf16 v[50:53], v[186:189], v[194:197], v[50:53]
	v_mfma_f32_16x16x32_bf16 v[38:41], v[178:181], v[202:205], v[38:41]
	v_mfma_f32_16x16x32_bf16 v[34:37], v[186:189], v[202:205], v[34:37]
	v_mfma_f32_16x16x32_bf16 v[22:25], v[178:181], v[210:213], v[22:25]
	v_mfma_f32_16x16x32_bf16 v[18:21], v[186:189], v[210:213], v[18:21]
	v_mfma_f32_16x16x32_bf16 v[6:9], v[178:181], v[218:221], v[6:9]
	s_barrier
	v_mfma_f32_16x16x32_bf16 v[2:5], v[186:189], v[218:221], v[2:5]
	s_setprio 0
	s_add_i32 s61, 0, 0x18000
	v_add_u32_e32 v142, s61, v157
	s_add_i32 s62, 0, 0x1c000
	ds_read_b128 v[130:133], v142
	ds_read_b128 v[152:155], v142 offset:1024
	ds_read_b128 v[166:169], v142 offset:2048
	ds_read_b128 v[170:173], v142 offset:3072
	v_add_u32_e32 v142, s62, v157
	ds_read_b128 v[174:177], v142
	ds_read_b128 v[178:181], v142 offset:1024
	ds_read_b128 v[182:185], v142 offset:2048
	ds_read_b128 v[186:189], v142 offset:3072
	s_add_u32 s44, s44, 0x40000
	s_addc_u32 s45, s45, 0
	s_mov_b32 m0, s50
	v_lshl_add_u64 v[228:229], s[44:45], 0, v[134:135]
	ds_read_b128 v[190:193], v161 offset:32768
	ds_read_b128 v[194:197], v161 offset:33792
	ds_read_b128 v[198:201], v161 offset:34816
	ds_read_b128 v[202:205], v161 offset:35840
	ds_read_b128 v[206:209], v161 offset:36864
	ds_read_b128 v[210:213], v161 offset:37888
	ds_read_b128 v[214:217], v161 offset:38912
	ds_read_b128 v[218:221], v161 offset:39936
	global_load_lds_dwordx4 v[228:229], off
	v_lshl_add_u64 v[228:229], s[44:45], 0, v[138:139]
	s_mov_b32 m0, s51
	s_nop 0
	global_load_lds_dwordx4 v[228:229], off
	s_waitcnt vmcnt(8)
	s_waitcnt lgkmcnt(0)
	s_barrier
	s_setprio 1
	s_waitcnt lgkmcnt(0)
	v_mfma_f32_16x16x32_bf16 v[126:129], v[130:133], v[190:193], v[126:129]
	v_mfma_f32_16x16x32_bf16 v[122:125], v[166:169], v[190:193], v[122:125]
	v_mfma_f32_16x16x32_bf16 v[110:113], v[130:133], v[198:201], v[110:113]
	v_mfma_f32_16x16x32_bf16 v[106:109], v[166:169], v[198:201], v[106:109]
	v_mfma_f32_16x16x32_bf16 v[94:97], v[130:133], v[206:209], v[94:97]
	v_mfma_f32_16x16x32_bf16 v[90:93], v[166:169], v[206:209], v[90:93]
	v_mfma_f32_16x16x32_bf16 v[78:81], v[130:133], v[214:217], v[78:81]
	v_mfma_f32_16x16x32_bf16 v[74:77], v[166:169], v[214:217], v[74:77]
	v_mfma_f32_16x16x32_bf16 v[126:129], v[152:155], v[194:197], v[126:129]
	v_mfma_f32_16x16x32_bf16 v[122:125], v[170:173], v[194:197], v[122:125]
	v_mfma_f32_16x16x32_bf16 v[110:113], v[152:155], v[202:205], v[110:113]
	v_mfma_f32_16x16x32_bf16 v[106:109], v[170:173], v[202:205], v[106:109]
	v_mfma_f32_16x16x32_bf16 v[94:97], v[152:155], v[210:213], v[94:97]
	v_mfma_f32_16x16x32_bf16 v[90:93], v[170:173], v[210:213], v[90:93]
	v_mfma_f32_16x16x32_bf16 v[78:81], v[152:155], v[218:221], v[78:81]
	v_mfma_f32_16x16x32_bf16 v[74:77], v[170:173], v[218:221], v[74:77]
	s_setprio 0
	s_setprio 1
	v_mfma_f32_16x16x32_bf16 v[118:121], v[174:177], v[190:193], v[118:121]
	v_mfma_f32_16x16x32_bf16 v[114:117], v[182:185], v[190:193], v[114:117]
	v_mfma_f32_16x16x32_bf16 v[102:105], v[174:177], v[198:201], v[102:105]
	v_mfma_f32_16x16x32_bf16 v[98:101], v[182:185], v[198:201], v[98:101]
	v_mfma_f32_16x16x32_bf16 v[86:89], v[174:177], v[206:209], v[86:89]
	v_mfma_f32_16x16x32_bf16 v[82:85], v[182:185], v[206:209], v[82:85]
	v_mfma_f32_16x16x32_bf16 v[70:73], v[174:177], v[214:217], v[70:73]
	v_mfma_f32_16x16x32_bf16 v[66:69], v[182:185], v[214:217], v[66:69]
	v_mfma_f32_16x16x32_bf16 v[118:121], v[178:181], v[194:197], v[118:121]
	v_mfma_f32_16x16x32_bf16 v[114:117], v[186:189], v[194:197], v[114:117]
	v_mfma_f32_16x16x32_bf16 v[102:105], v[178:181], v[202:205], v[102:105]
	v_mfma_f32_16x16x32_bf16 v[98:101], v[186:189], v[202:205], v[98:101]
	v_mfma_f32_16x16x32_bf16 v[86:89], v[178:181], v[210:213], v[86:89]
	v_mfma_f32_16x16x32_bf16 v[82:85], v[186:189], v[210:213], v[82:85]
	v_mfma_f32_16x16x32_bf16 v[70:73], v[178:181], v[218:221], v[70:73]
	s_barrier
; #define PG8_STAGE(bufoff, gbase, voff) do { _Pragma("unroll") for (int _i = 0; _i < 2; ++_i) \
;         __builtin_amdgcn_global_load_lds((const unsigned*)((const char*)(gbase) + (voff)[_i]), (PG8_LAS unsigned*)(lds + (bufoff) + ldsw + _i * 8192), 16, 0, 0); } while (0)
; #define PG8_LDA(dst, b, h) do { _Pragma("unroll") for (int m = 0; m < 4; ++m) _Pragma("unroll") for (int k = 0; k < 2; ++k) dst[m][k] = *(const PG8_LAS bf16x8*)(lds + PG8_SA(b, h) + aoff + m * 2048 + k * 1024); } while (0)
; #define PG8_MMA(ai, bj, At, Bt) do { __builtin_amdgcn_s_setprio(1); _Pragma("unroll") for (int m = 0; m < 4; ++m) _Pragma("unroll") for (int n = 0; n < 2; ++n) _Pragma("unroll") for (int k = 0; k < 2; ++k) \
;         acc[ai][bj][m][n] = __builtin_amdgcn_mfma_f32_16x16x32_bf16(Bt[n][k], At[m][k], acc[ai][bj][m][n], 0, 0, 0); __builtin_amdgcn_s_setprio(0); } while (0)
; #define PG8_WAIT_V(n) asm volatile("s_waitcnt vmcnt(" #n ")" ::: "memory")
; #define PG8_WAIT_L(n) asm volatile("s_waitcnt lgkmcnt(" #n ")" ::: "memory")
; #define PG8_BAR __builtin_amdgcn_s_barrier()
; #define PG8_SCHED __builtin_amdgcn_sched_barrier(0)
; template <class Epi, class Sched, bool ALIGN_EPI = false, bool SP2 = false>
; __device__ __forceinline__ void gemm_phase(PG8_LAS unsigned char* lds, const Gemm g, const Sched& S, const Epi& E) {
;     ...
;         for (int t = 0; t < nt; t += 2) {
;             const bool last = (t == nt - 2);
;             const char* a1 = cA + (size_t)(t + 1) * kstep;
;             const char* a2 = last ? nA : cA + (size_t)(t + 2) * kstep; const char* b2 = last ? nB : cB + (size_t)(t + 2) * kstep;
;             const char* a3 = a2 + kstep; const char* b3 = b2 + kstep;
;     ...
;             PG8_WAIT_V(8); PG8_WAIT_L(0); PG8_BAR; PG8_MMA(0, 0, At, B0); PG8_MMA(0, 1, At, B1); PG8_BAR; PG8_SCHED;
;             PG8_LDA(At, 1, 1); PG8_STAGE(PG8_SB(1, 0), b3, voffB); PG8_STAGE(PG8_SB(1, 1), b3 + hstep, voffB); PG8_STAGE(PG8_SA(1, 0), a3, voffA);
;             PG8_WAIT_V(8); PG8_WAIT_L(0); PG8_BAR; PG8_MMA(1, 0, At, B0); PG8_MMA(1, 1, At, B1); PG8_BAR; PG8_SCHED;
	v_mfma_f32_16x16x32_bf16 v[66:69], v[186:189], v[218:221], v[66:69]
	s_setprio 0
	s_add_i32 s44, s61, s33
	v_lshl_add_u64 v[162:163], v[162:163], 0, s[12:13]
	s_mov_b32 m0, s44
	s_nop 0
	global_load_lds_dwordx4 v[162:163], off
	s_add_i32 m0, s44, 0x2000
	s_add_u32 s42, s42, 0x40080
	v_lshl_add_u64 v[162:163], v[222:223], 0, s[12:13]
	s_addc_u32 s43, s43, 0
	s_add_i32 s44, s62, s33
	global_load_lds_dwordx4 v[162:163], off
	v_lshl_add_u64 v[162:163], s[42:43], 0, v[136:137]
	s_mov_b32 m0, s44
	s_nop 0
	global_load_lds_dwordx4 v[162:163], off
	v_lshl_add_u64 v[162:163], s[42:43], 0, v[140:141]
	s_add_i32 m0, s44, 0x2000
	s_nop 0
	global_load_lds_dwordx4 v[162:163], off
	v_lshl_add_u64 v[162:163], v[224:225], 0, s[12:13]
	s_mov_b32 m0, s52
	s_nop 0
	global_load_lds_dwordx4 v[162:163], off
	v_lshl_add_u64 v[162:163], v[226:227], 0, s[12:13]
	s_mov_b32 m0, s53
	s_nop 0
	global_load_lds_dwordx4 v[162:163], off
	ds_read_b128 v[190:193], v161 offset:49152
	ds_read_b128 v[194:197], v161 offset:50176
	ds_read_b128 v[198:201], v161 offset:51200
	ds_read_b128 v[202:205], v161 offset:52224
	ds_read_b128 v[206:209], v161 offset:53248
	ds_read_b128 v[210:213], v161 offset:54272
	ds_read_b128 v[214:217], v161 offset:55296
	ds_read_b128 v[218:221], v161 offset:56320
	s_waitcnt vmcnt(8)
	s_waitcnt lgkmcnt(0)
	s_barrier
	s_setprio 1
	s_waitcnt lgkmcnt(0)
	v_mfma_f32_16x16x32_bf16 v[62:65], v[130:133], v[190:193], v[62:65]
	v_mfma_f32_16x16x32_bf16 v[58:61], v[166:169], v[190:193], v[58:61]
	v_mfma_f32_16x16x32_bf16 v[46:49], v[130:133], v[198:201], v[46:49]
	v_mfma_f32_16x16x32_bf16 v[42:45], v[166:169], v[198:201], v[42:45]
	v_mfma_f32_16x16x32_bf16 v[30:33], v[130:133], v[206:209], v[30:33]
	v_mfma_f32_16x16x32_bf16 v[26:29], v[166:169], v[206:209], v[26:29]
	v_mfma_f32_16x16x32_bf16 v[14:17], v[130:133], v[214:217], v[14:17]
	v_mfma_f32_16x16x32_bf16 v[10:13], v[166:169], v[214:217], v[10:13]
	v_mfma_f32_16x16x32_bf16 v[62:65], v[152:155], v[194:197], v[62:65]
	v_mfma_f32_16x16x32_bf16 v[58:61], v[170:173], v[194:197], v[58:61]
	v_mfma_f32_16x16x32_bf16 v[46:49], v[152:155], v[202:205], v[46:49]
	v_mfma_f32_16x16x32_bf16 v[42:45], v[170:173], v[202:205], v[42:45]
	v_mfma_f32_16x16x32_bf16 v[30:33], v[152:155], v[210:213], v[30:33]
	v_mfma_f32_16x16x32_bf16 v[26:29], v[170:173], v[210:213], v[26:29]
	v_mfma_f32_16x16x32_bf16 v[14:17], v[152:155], v[218:221], v[14:17]
	v_mfma_f32_16x16x32_bf16 v[10:13], v[170:173], v[218:221], v[10:13]
	s_setprio 0
	s_setprio 1
	v_mfma_f32_16x16x32_bf16 v[54:57], v[174:177], v[190:193], v[54:57]
	v_mfma_f32_16x16x32_bf16 v[50:53], v[182:185], v[190:193], v[50:53]
	v_mfma_f32_16x16x32_bf16 v[38:41], v[174:177], v[198:201], v[38:41]
	v_mfma_f32_16x16x32_bf16 v[34:37], v[182:185], v[198:201], v[34:37]
	v_mfma_f32_16x16x32_bf16 v[22:25], v[174:177], v[206:209], v[22:25]
	v_mfma_f32_16x16x32_bf16 v[18:21], v[182:185], v[206:209], v[18:21]
	v_mfma_f32_16x16x32_bf16 v[6:9], v[174:177], v[214:217], v[6:9]
	v_mfma_f32_16x16x32_bf16 v[2:5], v[182:185], v[214:217], v[2:5]
	v_mfma_f32_16x16x32_bf16 v[54:57], v[178:181], v[194:197], v[54:57]
	v_mfma_f32_16x16x32_bf16 v[50:53], v[186:189], v[194:197], v[50:53]
	v_mfma_f32_16x16x32_bf16 v[38:41], v[178:181], v[202:205], v[38:41]
	v_mfma_f32_16x16x32_bf16 v[34:37], v[186:189], v[202:205], v[34:37]
	v_mfma_f32_16x16x32_bf16 v[22:25], v[178:181], v[210:213], v[22:25]
	v_mfma_f32_16x16x32_bf16 v[18:21], v[186:189], v[210:213], v[18:21]
	v_mfma_f32_16x16x32_bf16 v[6:9], v[178:181], v[218:221], v[6:9]
	s_barrier
	v_mfma_f32_16x16x32_bf16 v[2:5], v[186:189], v[218:221], v[2:5]
	s_setprio 0
	s_add_i32 s47, s47, 2
	s_add_u32 s4, s4, 0x100
	s_addc_u32 s5, s5, 0
	s_add_u32 s25, s25, 0x100
	s_addc_u32 s46, s46, 0
	s_cmp_gt_u32 s47, 13
	s_cbranch_scc0 .LBB0_811
	s_and_b64 vcc, exec, s[14:15]
	s_cbranch_vccz .LBB0_814
	s_barrier

; #define PG8_STAGE(bufoff, gbase, voff) do { _Pragma("unroll") for (int _i = 0; _i < 2; ++_i) \
;         __builtin_amdgcn_global_load_lds((const unsigned*)((const char*)(gbase) + (voff)[_i]), (PG8_LAS unsigned*)(lds + (bufoff) + ldsw + _i * 8192), 16, 0, 0); } while (0)
; #define PG8_LDA(dst, b, h) do { _Pragma("unroll") for (int m = 0; m < 4; ++m) _Pragma("unroll") for (int k = 0; k < 2; ++k) dst[m][k] = *(const PG8_LAS bf16x8*)(lds + PG8_SA(b, h) + aoff + m * 2048 + k * 1024); } while (0)
; #define PG8_LDB(dst, b, h) do { _Pragma("unroll") for (int n = 0; n < 2; ++n) _Pragma("unroll") for (int k = 0; k < 2; ++k) dst[n][k] = *(const PG8_LAS bf16x8*)(lds + PG8_SB(b, h) + boff + n * 2048 + k * 1024); } while (0)
; #define PG8_MMA(ai, bj, At, Bt) do { __builtin_amdgcn_s_setprio(1); _Pragma("unroll") for (int m = 0; m < 4; ++m) _Pragma("unroll") for (int n = 0; n < 2; ++n) _Pragma("unroll") for (int k = 0; k < 2; ++k) \
;         acc[ai][bj][m][n] = __builtin_amdgcn_mfma_f32_16x16x32_bf16(Bt[n][k], At[m][k], acc[ai][bj][m][n], 0, 0, 0); __builtin_amdgcn_s_setprio(0); } while (0)
; #define PG8_WAIT_V(n) asm volatile("s_waitcnt vmcnt(" #n ")" ::: "memory")
; #define PG8_BAR __builtin_amdgcn_s_barrier()
; template <class Epi, class Sched, bool ALIGN_EPI = false, bool SP2 = false>
; __device__ __forceinline__ void gemm_phase(PG8_LAS unsigned char* lds, const Gemm g, const Sched& S, const Epi& E) {
;     ...
;         for (int t = 0; t < nt; t += 2) {
;             const bool last = (t == nt - 2);
;             const char* a1 = cA + (size_t)(t + 1) * kstep;
;             const char* a2 = last ? nA : cA + (size_t)(t + 2) * kstep; const char* b2 = last ? nB : cB + (size_t)(t + 2) * kstep;
;             const char* a3 = a2 + kstep; const char* b3 = b2 + kstep;
;             if (last && has_next) S.a_ready(nxt);
;             if constexpr (SP2) {
;             PG8_LDB(B0, 0, 0); PG8_LDB(B1, 0, 1); PG8_SCHED; PG8_LDA(At, 0, 0); PG8_STAGE(PG8_SA(1, 1), a1 + hstep, voffA);
;             PG8_WAIT_V(8); PG8_WAIT_L(0); PG8_BAR; PG8_MMA(0, 0, At, B0); PG8_MMA(0, 1, At, B1); PG8_BAR; PG8_SCHED;
;             PG8_LDA(At, 0, 1); PG8_STAGE(PG8_SB(0, 0), b2, voffB); PG8_STAGE(PG8_SB(0, 1), b2 + hstep, voffB); PG8_STAGE(PG8_SA(0, 0), a2, voffA);
;             PG8_WAIT_V(8); PG8_WAIT_L(0); PG8_BAR; PG8_MMA(1, 0, At, B0); PG8_MMA(1, 1, At, B1); PG8_BAR; PG8_SCHED;
.LBB0_884:
	ds_read_b128 v[130:133], v159
	ds_read_b128 v[146:149], v159 offset:1024
	ds_read_b128 v[150:153], v159 offset:2048
	ds_read_b128 v[162:165], v159 offset:3072
	ds_read_b128 v[166:169], v160
	ds_read_b128 v[170:173], v160 offset:1024
	ds_read_b128 v[174:177], v160 offset:2048
	ds_read_b128 v[178:181], v160 offset:3072
	s_add_u32 s46, s44, 0xfffc0080
	s_addc_u32 s47, s45, -1
	s_cmp_eq_u32 s60, 12
	s_cselect_b32 s49, s35, s47
	s_cselect_b32 s48, s34, s46
	s_cselect_b32 s47, s17, s59
	s_cselect_b32 s46, s19, s58
	v_lshl_add_u64 v[214:215], s[44:45], 0, v[142:143]
	s_add_i32 m0, s50, 0xc000
	ds_read_b128 v[182:185], v161
	ds_read_b128 v[186:189], v161 offset:1024
	ds_read_b128 v[190:193], v161 offset:2048
	ds_read_b128 v[194:197], v161 offset:3072
	ds_read_b128 v[198:201], v161 offset:4096
	ds_read_b128 v[202:205], v161 offset:5120
	ds_read_b128 v[206:209], v161 offset:6144
	ds_read_b128 v[210:213], v161 offset:7168
	global_load_lds_dwordx4 v[214:215], off
	v_lshl_add_u64 v[214:215], s[44:45], 0, v[144:145]
	s_add_i32 m0, s50, 0xe000
	s_nop 0
	global_load_lds_dwordx4 v[214:215], off
	s_waitcnt vmcnt(8)
	s_waitcnt lgkmcnt(0)
	s_barrier
	s_setprio 1
	s_waitcnt lgkmcnt(0)
	v_mfma_f32_16x16x32_bf16 v[126:129], v[130:133], v[182:185], v[126:129]
	v_mfma_f32_16x16x32_bf16 v[122:125], v[150:153], v[182:185], v[122:125]
	v_mfma_f32_16x16x32_bf16 v[110:113], v[130:133], v[190:193], v[110:113]
	v_mfma_f32_16x16x32_bf16 v[106:109], v[150:153], v[190:193], v[106:109]
	v_mfma_f32_16x16x32_bf16 v[94:97], v[130:133], v[198:201], v[94:97]
	v_mfma_f32_16x16x32_bf16 v[90:93], v[150:153], v[198:201], v[90:93]
	v_mfma_f32_16x16x32_bf16 v[78:81], v[130:133], v[206:209], v[78:81]
	v_mfma_f32_16x16x32_bf16 v[74:77], v[150:153], v[206:209], v[74:77]
	v_mfma_f32_16x16x32_bf16 v[126:129], v[146:149], v[186:189], v[126:129]
	v_mfma_f32_16x16x32_bf16 v[122:125], v[162:165], v[186:189], v[122:125]
	v_mfma_f32_16x16x32_bf16 v[110:113], v[146:149], v[194:197], v[110:113]
	v_mfma_f32_16x16x32_bf16 v[106:109], v[162:165], v[194:197], v[106:109]
	v_mfma_f32_16x16x32_bf16 v[94:97], v[146:149], v[202:205], v[94:97]
	v_mfma_f32_16x16x32_bf16 v[90:93], v[162:165], v[202:205], v[90:93]
	v_mfma_f32_16x16x32_bf16 v[78:81], v[146:149], v[210:213], v[78:81]
	v_mfma_f32_16x16x32_bf16 v[74:77], v[162:165], v[210:213], v[74:77]
	s_setprio 0
	s_setprio 1
	v_mfma_f32_16x16x32_bf16 v[118:121], v[166:169], v[182:185], v[118:121]
	v_mfma_f32_16x16x32_bf16 v[114:117], v[174:177], v[182:185], v[114:117]
	v_mfma_f32_16x16x32_bf16 v[102:105], v[166:169], v[190:193], v[102:105]
	v_mfma_f32_16x16x32_bf16 v[98:101], v[174:177], v[190:193], v[98:101]
	v_mfma_f32_16x16x32_bf16 v[86:89], v[166:169], v[198:201], v[86:89]
	v_mfma_f32_16x16x32_bf16 v[82:85], v[174:177], v[198:201], v[82:85]
	v_mfma_f32_16x16x32_bf16 v[70:73], v[166:169], v[206:209], v[70:73]
	v_mfma_f32_16x16x32_bf16 v[66:69], v[174:177], v[206:209], v[66:69]
	v_mfma_f32_16x16x32_bf16 v[118:121], v[170:173], v[186:189], v[118:121]
	v_mfma_f32_16x16x32_bf16 v[114:117], v[178:181], v[186:189], v[114:117]
	v_mfma_f32_16x16x32_bf16 v[102:105], v[170:173], v[194:197], v[102:105]
	v_mfma_f32_16x16x32_bf16 v[98:101], v[178:181], v[194:197], v[98:101]
	v_mfma_f32_16x16x32_bf16 v[86:89], v[170:173], v[202:205], v[86:89]
	v_mfma_f32_16x16x32_bf16 v[82:85], v[178:181], v[202:205], v[82:85]
	v_mfma_f32_16x16x32_bf16 v[70:73], v[170:173], v[210:213], v[70:73]
	s_barrier
	v_mfma_f32_16x16x32_bf16 v[66:69], v[178:181], v[210:213], v[66:69]
	s_setprio 0
	s_add_i32 s61, s56, s33
	v_lshl_add_u64 v[214:215], s[46:47], 0, v[138:139]
	s_mov_b32 m0, s61
	s_nop 0
	global_load_lds_dwordx4 v[214:215], off
	s_add_i32 m0, s61, 0x2000
	s_add_u32 s62, s46, 0x40000
	v_lshl_add_u64 v[216:217], s[46:47], 0, v[134:135]
	s_addc_u32 s63, s47, 0
	s_add_i32 s61, s57, s33
	global_load_lds_dwordx4 v[216:217], off
	v_lshl_add_u64 v[218:219], s[62:63], 0, v[138:139]
	s_mov_b32 m0, s61
	v_lshl_add_u64 v[220:221], s[48:49], 0, v[136:137]
	global_load_lds_dwordx4 v[218:219], off
	v_lshl_add_u64 v[218:219], s[62:63], 0, v[134:135]
	s_add_i32 m0, s61, 0x2000
	s_nop 0
	global_load_lds_dwordx4 v[218:219], off
	v_lshl_add_u64 v[218:219], s[48:49], 0, v[140:141]
	s_mov_b32 m0, s50
	s_nop 0
	global_load_lds_dwordx4 v[218:219], off
	s_mov_b32 m0, s51
	s_nop 0
	global_load_lds_dwordx4 v[220:221], off
	ds_read_b128 v[182:185], v161 offset:16384
	ds_read_b128 v[186:189], v161 offset:17408
	ds_read_b128 v[190:193], v161 offset:18432
	ds_read_b128 v[194:197], v161 offset:19456
	ds_read_b128 v[198:201], v161 offset:20480
	ds_read_b128 v[202:205], v161 offset:21504
	ds_read_b128 v[206:209], v161 offset:22528
	ds_read_b128 v[210:213], v161 offset:23552
	s_waitcnt vmcnt(8)
	s_waitcnt lgkmcnt(0)
	s_barrier
; #define PG8_STAGE(bufoff, gbase, voff) do { _Pragma("unroll") for (int _i = 0; _i < 2; ++_i) \
;         __builtin_amdgcn_global_load_lds((const unsigned*)((const char*)(gbase) + (voff)[_i]), (PG8_LAS unsigned*)(lds + (bufoff) + ldsw + _i * 8192), 16, 0, 0); } while (0)
; #define PG8_LDA(dst, b, h) do { _Pragma("unroll") for (int m = 0; m < 4; ++m) _Pragma("unroll") for (int k = 0; k < 2; ++k) dst[m][k] = *(const PG8_LAS bf16x8*)(lds + PG8_SA(b, h) + aoff + m * 2048 + k * 1024); } while (0)
; #define PG8_LDB(dst, b, h) do { _Pragma("unroll") for (int n = 0; n < 2; ++n) _Pragma("unroll") for (int k = 0; k < 2; ++k) dst[n][k] = *(const PG8_LAS bf16x8*)(lds + PG8_SB(b, h) + boff + n * 2048 + k * 1024); } while (0)
; #define PG8_MMA(ai, bj, At, Bt) do { __builtin_amdgcn_s_setprio(1); _Pragma("unroll") for (int m = 0; m < 4; ++m) _Pragma("unroll") for (int n = 0; n < 2; ++n) _Pragma("unroll") for (int k = 0; k < 2; ++k) \
;         acc[ai][bj][m][n] = __builtin_amdgcn_mfma_f32_16x16x32_bf16(Bt[n][k], At[m][k], acc[ai][bj][m][n], 0, 0, 0); __builtin_amdgcn_s_setprio(0); } while (0)
; #define PG8_WAIT_V(n) asm volatile("s_waitcnt vmcnt(" #n ")" ::: "memory")
; #define PG8_WAIT_L(n) asm volatile("s_waitcnt lgkmcnt(" #n ")" ::: "memory")
; #define PG8_BAR __builtin_amdgcn_s_barrier()
; #define PG8_SCHED __builtin_amdgcn_sched_barrier(0)
; template <class Epi, class Sched, bool ALIGN_EPI = false, bool SP2 = false>
; __device__ __forceinline__ void gemm_phase(PG8_LAS unsigned char* lds, const Gemm g, const Sched& S, const Epi& E) {
;     ...
;             PG8_WAIT_V(8); PG8_WAIT_L(0); PG8_BAR; PG8_MMA(1, 0, At, B0); PG8_MMA(1, 1, At, B1); PG8_BAR; PG8_SCHED;
;             PG8_LDB(B0, 1, 0); PG8_LDB(B1, 1, 1); PG8_SCHED; PG8_LDA(At, 1, 0); PG8_STAGE(PG8_SA(0, 1), a2 + hstep, voffA);
;             PG8_WAIT_V(8); PG8_WAIT_L(0); PG8_BAR; PG8_MMA(0, 0, At, B0); PG8_MMA(0, 1, At, B1); PG8_BAR; PG8_SCHED;
	s_setprio 1
	s_waitcnt lgkmcnt(0)
	v_mfma_f32_16x16x32_bf16 v[62:65], v[130:133], v[182:185], v[62:65]
	v_mfma_f32_16x16x32_bf16 v[58:61], v[150:153], v[182:185], v[58:61]
	v_mfma_f32_16x16x32_bf16 v[46:49], v[130:133], v[190:193], v[46:49]
	v_mfma_f32_16x16x32_bf16 v[42:45], v[150:153], v[190:193], v[42:45]
	v_mfma_f32_16x16x32_bf16 v[30:33], v[130:133], v[198:201], v[30:33]
	v_mfma_f32_16x16x32_bf16 v[26:29], v[150:153], v[198:201], v[26:29]
	v_mfma_f32_16x16x32_bf16 v[14:17], v[130:133], v[206:209], v[14:17]
	v_mfma_f32_16x16x32_bf16 v[10:13], v[150:153], v[206:209], v[10:13]
	v_mfma_f32_16x16x32_bf16 v[62:65], v[146:149], v[186:189], v[62:65]
	v_mfma_f32_16x16x32_bf16 v[58:61], v[162:165], v[186:189], v[58:61]
	v_mfma_f32_16x16x32_bf16 v[46:49], v[146:149], v[194:197], v[46:49]
	v_mfma_f32_16x16x32_bf16 v[42:45], v[162:165], v[194:197], v[42:45]
	v_mfma_f32_16x16x32_bf16 v[30:33], v[146:149], v[202:205], v[30:33]
	v_mfma_f32_16x16x32_bf16 v[26:29], v[162:165], v[202:205], v[26:29]
	v_mfma_f32_16x16x32_bf16 v[14:17], v[146:149], v[210:213], v[14:17]
	v_mfma_f32_16x16x32_bf16 v[10:13], v[162:165], v[210:213], v[10:13]
	s_setprio 0
	s_setprio 1
	v_mfma_f32_16x16x32_bf16 v[54:57], v[166:169], v[182:185], v[54:57]
	v_mfma_f32_16x16x32_bf16 v[50:53], v[174:177], v[182:185], v[50:53]
	v_mfma_f32_16x16x32_bf16 v[38:41], v[166:169], v[190:193], v[38:41]
	v_mfma_f32_16x16x32_bf16 v[34:37], v[174:177], v[190:193], v[34:37]
	v_mfma_f32_16x16x32_bf16 v[22:25], v[166:169], v[198:201], v[22:25]
	v_mfma_f32_16x16x32_bf16 v[18:21], v[174:177], v[198:201], v[18:21]
	v_mfma_f32_16x16x32_bf16 v[6:9], v[166:169], v[206:209], v[6:9]
	v_mfma_f32_16x16x32_bf16 v[2:5], v[174:177], v[206:209], v[2:5]
	v_mfma_f32_16x16x32_bf16 v[54:57], v[170:173], v[186:189], v[54:57]
	v_mfma_f32_16x16x32_bf16 v[50:53], v[178:181], v[186:189], v[50:53]
	v_mfma_f32_16x16x32_bf16 v[38:41], v[170:173], v[194:197], v[38:41]
	v_mfma_f32_16x16x32_bf16 v[34:37], v[178:181], v[194:197], v[34:37]
	v_mfma_f32_16x16x32_bf16 v[22:25], v[170:173], v[202:205], v[22:25]
	v_mfma_f32_16x16x32_bf16 v[18:21], v[178:181], v[202:205], v[18:21]
	v_mfma_f32_16x16x32_bf16 v[6:9], v[170:173], v[210:213], v[6:9]
	s_barrier
	v_mfma_f32_16x16x32_bf16 v[2:5], v[178:181], v[210:213], v[2:5]
	s_setprio 0
	s_add_i32 s61, 0, 0x18000
	s_add_i32 s62, 0, 0x1c000
	v_add_u32_e32 v162, s61, v155
	v_add_u32_e32 v178, s62, v155
	ds_read_b128 v[130:133], v162
	ds_read_b128 v[146:149], v162 offset:1024
	ds_read_b128 v[150:153], v162 offset:2048
	ds_read_b128 v[162:165], v162 offset:3072
	ds_read_b128 v[166:169], v178
	ds_read_b128 v[170:173], v178 offset:1024
	ds_read_b128 v[174:177], v178 offset:2048
	ds_read_b128 v[178:181], v178 offset:3072
	s_add_u32 s48, s48, 0x40000
	s_addc_u32 s49, s49, 0
	s_mov_b32 m0, s52
	v_lshl_add_u64 v[222:223], s[48:49], 0, v[140:141]
	ds_read_b128 v[182:185], v161 offset:32768
	ds_read_b128 v[186:189], v161 offset:33792
	ds_read_b128 v[190:193], v161 offset:34816
	ds_read_b128 v[194:197], v161 offset:35840
	ds_read_b128 v[198:201], v161 offset:36864
	ds_read_b128 v[202:205], v161 offset:37888
	ds_read_b128 v[206:209], v161 offset:38912
	ds_read_b128 v[210:213], v161 offset:39936
	global_load_lds_dwordx4 v[222:223], off
	v_lshl_add_u64 v[222:223], s[48:49], 0, v[136:137]
	s_mov_b32 m0, s53
	s_nop 0
	global_load_lds_dwordx4 v[222:223], off
	s_waitcnt vmcnt(8)
	s_waitcnt lgkmcnt(0)
	s_barrier
	s_setprio 1
	s_waitcnt lgkmcnt(0)
	v_mfma_f32_16x16x32_bf16 v[126:129], v[130:133], v[182:185], v[126:129]
	v_mfma_f32_16x16x32_bf16 v[122:125], v[150:153], v[182:185], v[122:125]
	v_mfma_f32_16x16x32_bf16 v[110:113], v[130:133], v[190:193], v[110:113]
	v_mfma_f32_16x16x32_bf16 v[106:109], v[150:153], v[190:193], v[106:109]
	v_mfma_f32_16x16x32_bf16 v[94:97], v[130:133], v[198:201], v[94:97]
	v_mfma_f32_16x16x32_bf16 v[90:93], v[150:153], v[198:201], v[90:93]
	v_mfma_f32_16x16x32_bf16 v[78:81], v[130:133], v[206:209], v[78:81]
	v_mfma_f32_16x16x32_bf16 v[74:77], v[150:153], v[206:209], v[74:77]
	v_mfma_f32_16x16x32_bf16 v[126:129], v[146:149], v[186:189], v[126:129]
	v_mfma_f32_16x16x32_bf16 v[122:125], v[162:165], v[186:189], v[122:125]
	v_mfma_f32_16x16x32_bf16 v[110:113], v[146:149], v[194:197], v[110:113]
	v_mfma_f32_16x16x32_bf16 v[106:109], v[162:165], v[194:197], v[106:109]
	v_mfma_f32_16x16x32_bf16 v[94:97], v[146:149], v[202:205], v[94:97]
	v_mfma_f32_16x16x32_bf16 v[90:93], v[162:165], v[202:205], v[90:93]
	v_mfma_f32_16x16x32_bf16 v[78:81], v[146:149], v[210:213], v[78:81]
	v_mfma_f32_16x16x32_bf16 v[74:77], v[162:165], v[210:213], v[74:77]
	s_setprio 0
	s_setprio 1
	v_mfma_f32_16x16x32_bf16 v[118:121], v[166:169], v[182:185], v[118:121]
	v_mfma_f32_16x16x32_bf16 v[114:117], v[174:177], v[182:185], v[114:117]
	v_mfma_f32_16x16x32_bf16 v[102:105], v[166:169], v[190:193], v[102:105]
	v_mfma_f32_16x16x32_bf16 v[98:101], v[174:177], v[190:193], v[98:101]
	v_mfma_f32_16x16x32_bf16 v[86:89], v[166:169], v[198:201], v[86:89]
	v_mfma_f32_16x16x32_bf16 v[82:85], v[174:177], v[198:201], v[82:85]
	v_mfma_f32_16x16x32_bf16 v[70:73], v[166:169], v[206:209], v[70:73]
	v_mfma_f32_16x16x32_bf16 v[66:69], v[174:177], v[206:209], v[66:69]
	v_mfma_f32_16x16x32_bf16 v[118:121], v[170:173], v[186:189], v[118:121]
	v_mfma_f32_16x16x32_bf16 v[114:117], v[178:181], v[186:189], v[114:117]
	v_mfma_f32_16x16x32_bf16 v[102:105], v[170:173], v[194:197], v[102:105]
	v_mfma_f32_16x16x32_bf16 v[98:101], v[178:181], v[194:197], v[98:101]
	v_mfma_f32_16x16x32_bf16 v[86:89], v[170:173], v[202:205], v[86:89]
	v_mfma_f32_16x16x32_bf16 v[82:85], v[178:181], v[202:205], v[82:85]
	v_mfma_f32_16x16x32_bf16 v[70:73], v[170:173], v[210:213], v[70:73]
	s_barrier
; #define PG8_STAGE(bufoff, gbase, voff) do { _Pragma("unroll") for (int _i = 0; _i < 2; ++_i) \
;         __builtin_amdgcn_global_load_lds((const unsigned*)((const char*)(gbase) + (voff)[_i]), (PG8_LAS unsigned*)(lds + (bufoff) + ldsw + _i * 8192), 16, 0, 0); } while (0)
; #define PG8_LDA(dst, b, h) do { _Pragma("unroll") for (int m = 0; m < 4; ++m) _Pragma("unroll") for (int k = 0; k < 2; ++k) dst[m][k] = *(const PG8_LAS bf16x8*)(lds + PG8_SA(b, h) + aoff + m * 2048 + k * 1024); } while (0)
; #define PG8_MMA(ai, bj, At, Bt) do { __builtin_amdgcn_s_setprio(1); _Pragma("unroll") for (int m = 0; m < 4; ++m) _Pragma("unroll") for (int n = 0; n < 2; ++n) _Pragma("unroll") for (int k = 0; k < 2; ++k) \
;         acc[ai][bj][m][n] = __builtin_amdgcn_mfma_f32_16x16x32_bf16(Bt[n][k], At[m][k], acc[ai][bj][m][n], 0, 0, 0); __builtin_amdgcn_s_setprio(0); } while (0)
; #define PG8_WAIT_V(n) asm volatile("s_waitcnt vmcnt(" #n ")" ::: "memory")
; #define PG8_WAIT_L(n) asm volatile("s_waitcnt lgkmcnt(" #n ")" ::: "memory")
; #define PG8_BAR __builtin_amdgcn_s_barrier()
; #define PG8_SCHED __builtin_amdgcn_sched_barrier(0)
; template <class Epi, class Sched, bool ALIGN_EPI = false, bool SP2 = false>
; __device__ __forceinline__ void gemm_phase(PG8_LAS unsigned char* lds, const Gemm g, const Sched& S, const Epi& E) {
;     ...
;         for (int t = 0; t < nt; t += 2) {
;             const bool last = (t == nt - 2);
;             const char* a1 = cA + (size_t)(t + 1) * kstep;
;             const char* a2 = last ? nA : cA + (size_t)(t + 2) * kstep; const char* b2 = last ? nB : cB + (size_t)(t + 2) * kstep;
;             const char* a3 = a2 + kstep; const char* b3 = b2 + kstep;
;     ...
;             PG8_WAIT_V(8); PG8_WAIT_L(0); PG8_BAR; PG8_MMA(0, 0, At, B0); PG8_MMA(0, 1, At, B1); PG8_BAR; PG8_SCHED;
;             PG8_LDA(At, 1, 1); PG8_STAGE(PG8_SB(1, 0), b3, voffB); PG8_STAGE(PG8_SB(1, 1), b3 + hstep, voffB); PG8_STAGE(PG8_SA(1, 0), a3, voffA);
;             PG8_WAIT_V(8); PG8_WAIT_L(0); PG8_BAR; PG8_MMA(1, 0, At, B0); PG8_MMA(1, 1, At, B1); PG8_BAR; PG8_SCHED;
	v_mfma_f32_16x16x32_bf16 v[66:69], v[178:181], v[210:213], v[66:69]
	s_setprio 0
	s_add_i32 s48, s61, s33
	v_lshl_add_u64 v[214:215], v[214:215], 0, s[12:13]
	s_mov_b32 m0, s48
	s_nop 0
	global_load_lds_dwordx4 v[214:215], off
	s_add_i32 m0, s48, 0x2000
	s_add_u32 s46, s46, 0x40080
	v_lshl_add_u64 v[214:215], v[216:217], 0, s[12:13]
	s_addc_u32 s47, s47, 0
	s_add_i32 s48, s62, s33
	global_load_lds_dwordx4 v[214:215], off
	v_lshl_add_u64 v[214:215], s[46:47], 0, v[138:139]
	s_mov_b32 m0, s48
	s_nop 0
	global_load_lds_dwordx4 v[214:215], off
	v_lshl_add_u64 v[214:215], s[46:47], 0, v[134:135]
	s_add_i32 m0, s48, 0x2000
	s_nop 0
	global_load_lds_dwordx4 v[214:215], off
	v_lshl_add_u64 v[214:215], v[218:219], 0, s[12:13]
	s_mov_b32 m0, s54
	s_nop 0
	global_load_lds_dwordx4 v[214:215], off
	v_lshl_add_u64 v[214:215], v[220:221], 0, s[12:13]
	s_mov_b32 m0, s55
	s_nop 0
	global_load_lds_dwordx4 v[214:215], off
	ds_read_b128 v[182:185], v161 offset:49152
	ds_read_b128 v[186:189], v161 offset:50176
	ds_read_b128 v[190:193], v161 offset:51200
	ds_read_b128 v[194:197], v161 offset:52224
	ds_read_b128 v[198:201], v161 offset:53248
	ds_read_b128 v[202:205], v161 offset:54272
	ds_read_b128 v[206:209], v161 offset:55296
	ds_read_b128 v[210:213], v161 offset:56320
	s_waitcnt vmcnt(8)
	s_waitcnt lgkmcnt(0)
	s_barrier
	s_setprio 1
	s_waitcnt lgkmcnt(0)
	v_mfma_f32_16x16x32_bf16 v[62:65], v[130:133], v[182:185], v[62:65]
	v_mfma_f32_16x16x32_bf16 v[58:61], v[150:153], v[182:185], v[58:61]
	v_mfma_f32_16x16x32_bf16 v[46:49], v[130:133], v[190:193], v[46:49]
	v_mfma_f32_16x16x32_bf16 v[42:45], v[150:153], v[190:193], v[42:45]
	v_mfma_f32_16x16x32_bf16 v[30:33], v[130:133], v[198:201], v[30:33]
	v_mfma_f32_16x16x32_bf16 v[26:29], v[150:153], v[198:201], v[26:29]
	v_mfma_f32_16x16x32_bf16 v[14:17], v[130:133], v[206:209], v[14:17]
	v_mfma_f32_16x16x32_bf16 v[10:13], v[150:153], v[206:209], v[10:13]
	v_mfma_f32_16x16x32_bf16 v[62:65], v[146:149], v[186:189], v[62:65]
	v_mfma_f32_16x16x32_bf16 v[58:61], v[162:165], v[186:189], v[58:61]
	v_mfma_f32_16x16x32_bf16 v[46:49], v[146:149], v[194:197], v[46:49]
	v_mfma_f32_16x16x32_bf16 v[42:45], v[162:165], v[194:197], v[42:45]
	v_mfma_f32_16x16x32_bf16 v[30:33], v[146:149], v[202:205], v[30:33]
	v_mfma_f32_16x16x32_bf16 v[26:29], v[162:165], v[202:205], v[26:29]
	v_mfma_f32_16x16x32_bf16 v[14:17], v[146:149], v[210:213], v[14:17]
	v_mfma_f32_16x16x32_bf16 v[10:13], v[162:165], v[210:213], v[10:13]
	s_setprio 0
	s_setprio 1
	v_mfma_f32_16x16x32_bf16 v[54:57], v[166:169], v[182:185], v[54:57]
	v_mfma_f32_16x16x32_bf16 v[50:53], v[174:177], v[182:185], v[50:53]
	v_mfma_f32_16x16x32_bf16 v[38:41], v[166:169], v[190:193], v[38:41]
	v_mfma_f32_16x16x32_bf16 v[34:37], v[174:177], v[190:193], v[34:37]
	v_mfma_f32_16x16x32_bf16 v[22:25], v[166:169], v[198:201], v[22:25]
	v_mfma_f32_16x16x32_bf16 v[18:21], v[174:177], v[198:201], v[18:21]
	v_mfma_f32_16x16x32_bf16 v[6:9], v[166:169], v[206:209], v[6:9]
	v_mfma_f32_16x16x32_bf16 v[2:5], v[174:177], v[206:209], v[2:5]
	v_mfma_f32_16x16x32_bf16 v[54:57], v[170:173], v[186:189], v[54:57]
	v_mfma_f32_16x16x32_bf16 v[50:53], v[178:181], v[186:189], v[50:53]
	v_mfma_f32_16x16x32_bf16 v[38:41], v[170:173], v[194:197], v[38:41]
	v_mfma_f32_16x16x32_bf16 v[34:37], v[178:181], v[194:197], v[34:37]
	v_mfma_f32_16x16x32_bf16 v[22:25], v[170:173], v[202:205], v[22:25]
	v_mfma_f32_16x16x32_bf16 v[18:21], v[178:181], v[202:205], v[18:21]
	v_mfma_f32_16x16x32_bf16 v[6:9], v[170:173], v[210:213], v[6:9]
	s_barrier
	v_mfma_f32_16x16x32_bf16 v[2:5], v[178:181], v[210:213], v[2:5]
	s_setprio 0
	s_add_i32 s60, s60, 2
	s_add_u32 s44, s44, 0x100
	s_addc_u32 s45, s45, 0
	s_add_u32 s58, s58, 0x100
	s_addc_u32 s59, s59, 0
	s_cmp_gt_u32 s60, 13
	s_cbranch_scc0 .LBB0_884
	s_and_b64 vcc, exec, s[14:15]
	s_cbranch_vccz .LBB0_887
	s_barrier

; #define PG8_STAGE(bufoff, gbase, voff) do { _Pragma("unroll") for (int _i = 0; _i < 2; ++_i) \
;         __builtin_amdgcn_global_load_lds((const unsigned*)((const char*)(gbase) + (voff)[_i]), (PG8_LAS unsigned*)(lds + (bufoff) + ldsw + _i * 8192), 16, 0, 0); } while (0)
; #define PG8_LDA(dst, b, h) do { _Pragma("unroll") for (int m = 0; m < 4; ++m) _Pragma("unroll") for (int k = 0; k < 2; ++k) dst[m][k] = *(const PG8_LAS bf16x8*)(lds + PG8_SA(b, h) + aoff + m * 2048 + k * 1024); } while (0)
; #define PG8_LDB(dst, b, h) do { _Pragma("unroll") for (int n = 0; n < 2; ++n) _Pragma("unroll") for (int k = 0; k < 2; ++k) dst[n][k] = *(const PG8_LAS bf16x8*)(lds + PG8_SB(b, h) + boff + n * 2048 + k * 1024); } while (0)
; #define PG8_MMA(ai, bj, At, Bt) do { __builtin_amdgcn_s_setprio(1); _Pragma("unroll") for (int m = 0; m < 4; ++m) _Pragma("unroll") for (int n = 0; n < 2; ++n) _Pragma("unroll") for (int k = 0; k < 2; ++k) \
;         acc[ai][bj][m][n] = __builtin_amdgcn_mfma_f32_16x16x32_bf16(Bt[n][k], At[m][k], acc[ai][bj][m][n], 0, 0, 0); __builtin_amdgcn_s_setprio(0); } while (0)
; #define PG8_WAIT_V(n) asm volatile("s_waitcnt vmcnt(" #n ")" ::: "memory")
; #define PG8_WAIT_L(n) asm volatile("s_waitcnt lgkmcnt(" #n ")" ::: "memory")
; #define PG8_BAR __builtin_amdgcn_s_barrier()
; template <class Epi, class Sched, bool ALIGN_EPI = false, bool SP2 = false>
; __device__ __forceinline__ void gemm_phase(PG8_LAS unsigned char* lds, const Gemm g, const Sched& S, const Epi& E) {
;     ...
;             const char* a1 = cA + (size_t)(t + 1) * kstep;
;             const char* a2 = last ? nA : cA + (size_t)(t + 2) * kstep; const char* b2 = last ? nB : cB + (size_t)(t + 2) * kstep;
;             const char* a3 = a2 + kstep; const char* b3 = b2 + kstep;
;             if (last && has_next) S.a_ready(nxt);
;             if constexpr (SP2) {
;             PG8_LDB(B0, 0, 0); PG8_LDB(B1, 0, 1); PG8_SCHED; PG8_LDA(At, 0, 0); PG8_STAGE(PG8_SA(1, 1), a1 + hstep, voffA);
;             PG8_WAIT_V(8); PG8_WAIT_L(0); PG8_BAR; PG8_MMA(0, 0, At, B0); PG8_MMA(0, 1, At, B1); PG8_BAR; PG8_SCHED;
;             PG8_LDA(At, 0, 1); PG8_STAGE(PG8_SB(0, 0), b2, voffB); PG8_STAGE(PG8_SB(0, 1), b2 + hstep, voffB); PG8_STAGE(PG8_SA(0, 0), a2, voffA);
;             PG8_WAIT_V(8); PG8_WAIT_L(0); PG8_BAR; PG8_MMA(1, 0, At, B0); PG8_MMA(1, 1, At, B1); PG8_BAR; PG8_SCHED;
.LBB0_968:
	v_add_u32_e32 v162, s45, v148
	v_add_u32_e32 v178, s46, v148
	s_add_u32 s22, s8, s20
	ds_read_b128 v[150:153], v162
	ds_read_b128 v[154:157], v162 offset:1024
	ds_read_b128 v[158:161], v162 offset:2048
	ds_read_b128 v[162:165], v162 offset:3072
	ds_read_b128 v[166:169], v178
	ds_read_b128 v[170:173], v178 offset:1024
	ds_read_b128 v[174:177], v178 offset:2048
	ds_read_b128 v[178:181], v178 offset:3072
	s_addc_u32 s23, s9, s21
	s_add_u32 s22, s22, 0x100
	s_addc_u32 s23, s23, 0
	s_add_u32 s51, s48, s20
	s_addc_u32 s52, s49, s21
	s_cmpk_eq_i32 s20, 0x700
	s_cselect_b32 s25, s19, s23
	s_cselect_b32 s24, s18, s22
	s_cselect_b32 s23, s13, s52
	s_cselect_b32 s22, s15, s51
	v_lshl_add_u64 v[214:215], v[142:143], 0, s[20:21]
	s_add_i32 m0, s5, 0xc000
	ds_read_b128 v[182:185], v149
	ds_read_b128 v[186:189], v149 offset:1024
	ds_read_b128 v[190:193], v149 offset:2048
	ds_read_b128 v[194:197], v149 offset:3072
	ds_read_b128 v[198:201], v149 offset:4096
	ds_read_b128 v[202:205], v149 offset:5120
	ds_read_b128 v[206:209], v149 offset:6144
	ds_read_b128 v[210:213], v149 offset:7168
	global_load_lds_dwordx4 v[214:215], off
	v_lshl_add_u64 v[214:215], v[144:145], 0, s[20:21]
	s_add_i32 m0, s5, 0xe000
	s_nop 0
	global_load_lds_dwordx4 v[214:215], off
	s_waitcnt vmcnt(8)
	s_waitcnt lgkmcnt(0)
	s_barrier
	s_setprio 1
	s_waitcnt lgkmcnt(0)
	v_mfma_f32_16x16x32_bf16 v[126:129], v[150:153], v[182:185], v[126:129]
	v_mfma_f32_16x16x32_bf16 v[122:125], v[158:161], v[182:185], v[122:125]
	v_mfma_f32_16x16x32_bf16 v[114:117], v[150:153], v[190:193], v[114:117]
	v_mfma_f32_16x16x32_bf16 v[106:109], v[158:161], v[190:193], v[106:109]
	v_mfma_f32_16x16x32_bf16 v[98:101], v[150:153], v[198:201], v[98:101]
	v_mfma_f32_16x16x32_bf16 v[90:93], v[158:161], v[198:201], v[90:93]
	v_mfma_f32_16x16x32_bf16 v[82:85], v[150:153], v[206:209], v[82:85]
	v_mfma_f32_16x16x32_bf16 v[74:77], v[158:161], v[206:209], v[74:77]
	v_mfma_f32_16x16x32_bf16 v[126:129], v[154:157], v[186:189], v[126:129]
	v_mfma_f32_16x16x32_bf16 v[122:125], v[162:165], v[186:189], v[122:125]
	v_mfma_f32_16x16x32_bf16 v[114:117], v[154:157], v[194:197], v[114:117]
	v_mfma_f32_16x16x32_bf16 v[106:109], v[162:165], v[194:197], v[106:109]
	v_mfma_f32_16x16x32_bf16 v[98:101], v[154:157], v[202:205], v[98:101]
	v_mfma_f32_16x16x32_bf16 v[90:93], v[162:165], v[202:205], v[90:93]
	v_mfma_f32_16x16x32_bf16 v[82:85], v[154:157], v[210:213], v[82:85]
	v_mfma_f32_16x16x32_bf16 v[74:77], v[162:165], v[210:213], v[74:77]
	s_setprio 0
	s_setprio 1
	v_mfma_f32_16x16x32_bf16 v[118:121], v[166:169], v[182:185], v[118:121]
	v_mfma_f32_16x16x32_bf16 v[110:113], v[174:177], v[182:185], v[110:113]
	v_mfma_f32_16x16x32_bf16 v[102:105], v[166:169], v[190:193], v[102:105]
	v_mfma_f32_16x16x32_bf16 v[94:97], v[174:177], v[190:193], v[94:97]
	v_mfma_f32_16x16x32_bf16 v[86:89], v[166:169], v[198:201], v[86:89]
	v_mfma_f32_16x16x32_bf16 v[78:81], v[174:177], v[198:201], v[78:81]
	v_mfma_f32_16x16x32_bf16 v[70:73], v[166:169], v[206:209], v[70:73]
	v_mfma_f32_16x16x32_bf16 v[66:69], v[174:177], v[206:209], v[66:69]
	v_mfma_f32_16x16x32_bf16 v[118:121], v[170:173], v[186:189], v[118:121]
	v_mfma_f32_16x16x32_bf16 v[110:113], v[178:181], v[186:189], v[110:113]
	v_mfma_f32_16x16x32_bf16 v[102:105], v[170:173], v[194:197], v[102:105]
	v_mfma_f32_16x16x32_bf16 v[94:97], v[178:181], v[194:197], v[94:97]
	v_mfma_f32_16x16x32_bf16 v[86:89], v[170:173], v[202:205], v[86:89]
	v_mfma_f32_16x16x32_bf16 v[78:81], v[178:181], v[202:205], v[78:81]
	v_mfma_f32_16x16x32_bf16 v[70:73], v[170:173], v[210:213], v[70:73]
	s_barrier
	v_mfma_f32_16x16x32_bf16 v[66:69], v[178:181], v[210:213], v[66:69]
	s_setprio 0
	s_add_i32 s51, s45, s38
	v_lshl_add_u64 v[214:215], s[22:23], 0, v[130:131]
	s_mov_b32 m0, s51
	s_nop 0
	global_load_lds_dwordx4 v[214:215], off
	s_add_i32 m0, s51, 0x2000
	s_add_u32 s52, s22, 0x40000
	v_lshl_add_u64 v[216:217], s[22:23], 0, v[132:133]
	s_addc_u32 s53, s23, 0
	s_add_i32 s51, s46, s38
	global_load_lds_dwordx4 v[216:217], off
	v_lshl_add_u64 v[218:219], s[52:53], 0, v[130:131]
	s_mov_b32 m0, s51
	v_lshl_add_u64 v[220:221], s[24:25], 0, v[132:133]
	global_load_lds_dwordx4 v[218:219], off
	v_lshl_add_u64 v[218:219], s[52:53], 0, v[132:133]
	s_add_i32 m0, s51, 0x2000
	s_nop 0
	global_load_lds_dwordx4 v[218:219], off
	v_lshl_add_u64 v[218:219], s[24:25], 0, v[130:131]
	s_mov_b32 m0, s5
	s_nop 0
	global_load_lds_dwordx4 v[218:219], off
	s_mov_b32 m0, s39
	s_nop 0
	global_load_lds_dwordx4 v[220:221], off
	ds_read_b128 v[182:185], v149 offset:16384
	ds_read_b128 v[186:189], v149 offset:17408
	ds_read_b128 v[190:193], v149 offset:18432
	ds_read_b128 v[194:197], v149 offset:19456
	ds_read_b128 v[198:201], v149 offset:20480
	ds_read_b128 v[202:205], v149 offset:21504
	ds_read_b128 v[206:209], v149 offset:22528
	ds_read_b128 v[210:213], v149 offset:23552
	s_waitcnt vmcnt(8)
	s_waitcnt lgkmcnt(0)
	s_barrier
; #define PG8_STAGE(bufoff, gbase, voff) do { _Pragma("unroll") for (int _i = 0; _i < 2; ++_i) \
;         __builtin_amdgcn_global_load_lds((const unsigned*)((const char*)(gbase) + (voff)[_i]), (PG8_LAS unsigned*)(lds + (bufoff) + ldsw + _i * 8192), 16, 0, 0); } while (0)
; #define PG8_LDA(dst, b, h) do { _Pragma("unroll") for (int m = 0; m < 4; ++m) _Pragma("unroll") for (int k = 0; k < 2; ++k) dst[m][k] = *(const PG8_LAS bf16x8*)(lds + PG8_SA(b, h) + aoff + m * 2048 + k * 1024); } while (0)
; #define PG8_LDB(dst, b, h) do { _Pragma("unroll") for (int n = 0; n < 2; ++n) _Pragma("unroll") for (int k = 0; k < 2; ++k) dst[n][k] = *(const PG8_LAS bf16x8*)(lds + PG8_SB(b, h) + boff + n * 2048 + k * 1024); } while (0)
; #define PG8_MMA(ai, bj, At, Bt) do { __builtin_amdgcn_s_setprio(1); _Pragma("unroll") for (int m = 0; m < 4; ++m) _Pragma("unroll") for (int n = 0; n < 2; ++n) _Pragma("unroll") for (int k = 0; k < 2; ++k) \
;         acc[ai][bj][m][n] = __builtin_amdgcn_mfma_f32_16x16x32_bf16(Bt[n][k], At[m][k], acc[ai][bj][m][n], 0, 0, 0); __builtin_amdgcn_s_setprio(0); } while (0)
; #define PG8_WAIT_V(n) asm volatile("s_waitcnt vmcnt(" #n ")" ::: "memory")
; #define PG8_WAIT_L(n) asm volatile("s_waitcnt lgkmcnt(" #n ")" ::: "memory")
; #define PG8_BAR __builtin_amdgcn_s_barrier()
; #define PG8_SCHED __builtin_amdgcn_sched_barrier(0)
; template <class Epi, class Sched, bool ALIGN_EPI = false, bool SP2 = false>
; __device__ __forceinline__ void gemm_phase(PG8_LAS unsigned char* lds, const Gemm g, const Sched& S, const Epi& E) {
;     ...
;             PG8_WAIT_V(8); PG8_WAIT_L(0); PG8_BAR; PG8_MMA(1, 0, At, B0); PG8_MMA(1, 1, At, B1); PG8_BAR; PG8_SCHED;
;             PG8_LDB(B0, 1, 0); PG8_LDB(B1, 1, 1); PG8_SCHED; PG8_LDA(At, 1, 0); PG8_STAGE(PG8_SA(0, 1), a2 + hstep, voffA);
;             PG8_WAIT_V(8); PG8_WAIT_L(0); PG8_BAR; PG8_MMA(0, 0, At, B0); PG8_MMA(0, 1, At, B1); PG8_BAR; PG8_SCHED;
	s_setprio 1
	s_waitcnt lgkmcnt(0)
	v_mfma_f32_16x16x32_bf16 v[62:65], v[150:153], v[182:185], v[62:65]
	v_mfma_f32_16x16x32_bf16 v[58:61], v[158:161], v[182:185], v[58:61]
	v_mfma_f32_16x16x32_bf16 v[50:53], v[150:153], v[190:193], v[50:53]
	v_mfma_f32_16x16x32_bf16 v[42:45], v[158:161], v[190:193], v[42:45]
	v_mfma_f32_16x16x32_bf16 v[34:37], v[150:153], v[198:201], v[34:37]
	v_mfma_f32_16x16x32_bf16 v[26:29], v[158:161], v[198:201], v[26:29]
	v_mfma_f32_16x16x32_bf16 v[18:21], v[150:153], v[206:209], v[18:21]
	v_mfma_f32_16x16x32_bf16 v[10:13], v[158:161], v[206:209], v[10:13]
	v_mfma_f32_16x16x32_bf16 v[62:65], v[154:157], v[186:189], v[62:65]
	v_mfma_f32_16x16x32_bf16 v[58:61], v[162:165], v[186:189], v[58:61]
	v_mfma_f32_16x16x32_bf16 v[50:53], v[154:157], v[194:197], v[50:53]
	v_mfma_f32_16x16x32_bf16 v[42:45], v[162:165], v[194:197], v[42:45]
	v_mfma_f32_16x16x32_bf16 v[34:37], v[154:157], v[202:205], v[34:37]
	v_mfma_f32_16x16x32_bf16 v[26:29], v[162:165], v[202:205], v[26:29]
	v_mfma_f32_16x16x32_bf16 v[18:21], v[154:157], v[210:213], v[18:21]
	v_mfma_f32_16x16x32_bf16 v[10:13], v[162:165], v[210:213], v[10:13]
	s_setprio 0
	s_setprio 1
	v_mfma_f32_16x16x32_bf16 v[54:57], v[166:169], v[182:185], v[54:57]
	v_mfma_f32_16x16x32_bf16 v[46:49], v[174:177], v[182:185], v[46:49]
	v_mfma_f32_16x16x32_bf16 v[38:41], v[166:169], v[190:193], v[38:41]
	v_mfma_f32_16x16x32_bf16 v[30:33], v[174:177], v[190:193], v[30:33]
	v_mfma_f32_16x16x32_bf16 v[22:25], v[166:169], v[198:201], v[22:25]
	v_mfma_f32_16x16x32_bf16 v[14:17], v[174:177], v[198:201], v[14:17]
	v_mfma_f32_16x16x32_bf16 v[6:9], v[166:169], v[206:209], v[6:9]
	v_mfma_f32_16x16x32_bf16 v[2:5], v[174:177], v[206:209], v[2:5]
	v_mfma_f32_16x16x32_bf16 v[54:57], v[170:173], v[186:189], v[54:57]
	v_mfma_f32_16x16x32_bf16 v[46:49], v[178:181], v[186:189], v[46:49]
	v_mfma_f32_16x16x32_bf16 v[38:41], v[170:173], v[194:197], v[38:41]
	v_mfma_f32_16x16x32_bf16 v[30:33], v[178:181], v[194:197], v[30:33]
	v_mfma_f32_16x16x32_bf16 v[22:25], v[170:173], v[202:205], v[22:25]
	v_mfma_f32_16x16x32_bf16 v[14:17], v[178:181], v[202:205], v[14:17]
	v_mfma_f32_16x16x32_bf16 v[6:9], v[170:173], v[210:213], v[6:9]
	s_barrier
	v_mfma_f32_16x16x32_bf16 v[2:5], v[178:181], v[210:213], v[2:5]
	s_setprio 0
	s_add_i32 s51, 0, 0x18000
	s_add_i32 s52, 0, 0x1c000
	v_add_u32_e32 v162, s51, v148
	v_add_u32_e32 v178, s52, v148
	ds_read_b128 v[150:153], v162
	ds_read_b128 v[154:157], v162 offset:1024
	ds_read_b128 v[158:161], v162 offset:2048
	ds_read_b128 v[162:165], v162 offset:3072
	ds_read_b128 v[166:169], v178
	ds_read_b128 v[170:173], v178 offset:1024
	ds_read_b128 v[174:177], v178 offset:2048
	ds_read_b128 v[178:181], v178 offset:3072
	s_add_u32 s24, s24, 0x40000
	s_addc_u32 s25, s25, 0
	s_mov_b32 m0, s40
	v_lshl_add_u64 v[222:223], s[24:25], 0, v[130:131]
	ds_read_b128 v[182:185], v149 offset:32768
	ds_read_b128 v[186:189], v149 offset:33792
	ds_read_b128 v[190:193], v149 offset:34816
	ds_read_b128 v[194:197], v149 offset:35840
	ds_read_b128 v[198:201], v149 offset:36864
	ds_read_b128 v[202:205], v149 offset:37888
	ds_read_b128 v[206:209], v149 offset:38912
	ds_read_b128 v[210:213], v149 offset:39936
	global_load_lds_dwordx4 v[222:223], off
	v_lshl_add_u64 v[222:223], s[24:25], 0, v[132:133]
	s_mov_b32 m0, s41
	s_nop 0
	global_load_lds_dwordx4 v[222:223], off
	s_waitcnt vmcnt(8)
	s_waitcnt lgkmcnt(0)
	s_barrier
	s_setprio 1
	s_waitcnt lgkmcnt(0)
	v_mfma_f32_16x16x32_bf16 v[126:129], v[150:153], v[182:185], v[126:129]
	v_mfma_f32_16x16x32_bf16 v[122:125], v[158:161], v[182:185], v[122:125]
	v_mfma_f32_16x16x32_bf16 v[114:117], v[150:153], v[190:193], v[114:117]
	v_mfma_f32_16x16x32_bf16 v[106:109], v[158:161], v[190:193], v[106:109]
	v_mfma_f32_16x16x32_bf16 v[98:101], v[150:153], v[198:201], v[98:101]
	v_mfma_f32_16x16x32_bf16 v[90:93], v[158:161], v[198:201], v[90:93]
	v_mfma_f32_16x16x32_bf16 v[82:85], v[150:153], v[206:209], v[82:85]
	v_mfma_f32_16x16x32_bf16 v[74:77], v[158:161], v[206:209], v[74:77]
	v_mfma_f32_16x16x32_bf16 v[126:129], v[154:157], v[186:189], v[126:129]
	v_mfma_f32_16x16x32_bf16 v[122:125], v[162:165], v[186:189], v[122:125]
	v_mfma_f32_16x16x32_bf16 v[114:117], v[154:157], v[194:197], v[114:117]
	v_mfma_f32_16x16x32_bf16 v[106:109], v[162:165], v[194:197], v[106:109]
	v_mfma_f32_16x16x32_bf16 v[98:101], v[154:157], v[202:205], v[98:101]
	v_mfma_f32_16x16x32_bf16 v[90:93], v[162:165], v[202:205], v[90:93]
	v_mfma_f32_16x16x32_bf16 v[82:85], v[154:157], v[210:213], v[82:85]
	v_mfma_f32_16x16x32_bf16 v[74:77], v[162:165], v[210:213], v[74:77]
	s_setprio 0
	s_setprio 1
	v_mfma_f32_16x16x32_bf16 v[118:121], v[166:169], v[182:185], v[118:121]
	v_mfma_f32_16x16x32_bf16 v[110:113], v[174:177], v[182:185], v[110:113]
	v_mfma_f32_16x16x32_bf16 v[102:105], v[166:169], v[190:193], v[102:105]
	v_mfma_f32_16x16x32_bf16 v[94:97], v[174:177], v[190:193], v[94:97]
	v_mfma_f32_16x16x32_bf16 v[86:89], v[166:169], v[198:201], v[86:89]
	v_mfma_f32_16x16x32_bf16 v[78:81], v[174:177], v[198:201], v[78:81]
	v_mfma_f32_16x16x32_bf16 v[70:73], v[166:169], v[206:209], v[70:73]
	v_mfma_f32_16x16x32_bf16 v[66:69], v[174:177], v[206:209], v[66:69]
	v_mfma_f32_16x16x32_bf16 v[118:121], v[170:173], v[186:189], v[118:121]
	v_mfma_f32_16x16x32_bf16 v[110:113], v[178:181], v[186:189], v[110:113]
	v_mfma_f32_16x16x32_bf16 v[102:105], v[170:173], v[194:197], v[102:105]
	v_mfma_f32_16x16x32_bf16 v[94:97], v[178:181], v[194:197], v[94:97]
	v_mfma_f32_16x16x32_bf16 v[86:89], v[170:173], v[202:205], v[86:89]
	v_mfma_f32_16x16x32_bf16 v[78:81], v[178:181], v[202:205], v[78:81]
	v_mfma_f32_16x16x32_bf16 v[70:73], v[170:173], v[210:213], v[70:73]
	s_barrier
; #define PG8_STAGE(bufoff, gbase, voff) do { _Pragma("unroll") for (int _i = 0; _i < 2; ++_i) \
;         __builtin_amdgcn_global_load_lds((const unsigned*)((const char*)(gbase) + (voff)[_i]), (PG8_LAS unsigned*)(lds + (bufoff) + ldsw + _i * 8192), 16, 0, 0); } while (0)
; #define PG8_LDA(dst, b, h) do { _Pragma("unroll") for (int m = 0; m < 4; ++m) _Pragma("unroll") for (int k = 0; k < 2; ++k) dst[m][k] = *(const PG8_LAS bf16x8*)(lds + PG8_SA(b, h) + aoff + m * 2048 + k * 1024); } while (0)
; #define PG8_MMA(ai, bj, At, Bt) do { __builtin_amdgcn_s_setprio(1); _Pragma("unroll") for (int m = 0; m < 4; ++m) _Pragma("unroll") for (int n = 0; n < 2; ++n) _Pragma("unroll") for (int k = 0; k < 2; ++k) \
;         acc[ai][bj][m][n] = __builtin_amdgcn_mfma_f32_16x16x32_bf16(Bt[n][k], At[m][k], acc[ai][bj][m][n], 0, 0, 0); __builtin_amdgcn_s_setprio(0); } while (0)
; #define PG8_WAIT_V(n) asm volatile("s_waitcnt vmcnt(" #n ")" ::: "memory")
; #define PG8_WAIT_L(n) asm volatile("s_waitcnt lgkmcnt(" #n ")" ::: "memory")
; #define PG8_BAR __builtin_amdgcn_s_barrier()
; #define PG8_SCHED __builtin_amdgcn_sched_barrier(0)
; template <class Epi, class Sched, bool ALIGN_EPI = false, bool SP2 = false>
; __device__ __forceinline__ void gemm_phase(PG8_LAS unsigned char* lds, const Gemm g, const Sched& S, const Epi& E) {
;     ...
;             PG8_LDA(At, 1, 1); PG8_STAGE(PG8_SB(1, 0), b3, voffB); PG8_STAGE(PG8_SB(1, 1), b3 + hstep, voffB); PG8_STAGE(PG8_SA(1, 0), a3, voffA);
;             PG8_WAIT_V(8); PG8_WAIT_L(0); PG8_BAR; PG8_MMA(1, 0, At, B0); PG8_MMA(1, 1, At, B1); PG8_BAR; PG8_SCHED;
;     ...
;         if (!has_next) break;
; #pragma unroll
;         for (int a = 0; a < 2; ++a)
; #pragma unroll
;             for (int b = 0; b < 2; ++b)
; #pragma unroll
;                 for (int m = 0; m < 4; ++m)
; #pragma unroll
;                     for (int n = 0; n < 2; ++n) acc[a][b][m][n] = (f32x4){0.f, 0.f, 0.f, 0.f};
;         cur = nxt; cA = nA; cB = nB; ++ui;
	v_mfma_f32_16x16x32_bf16 v[66:69], v[178:181], v[210:213], v[66:69]
	s_setprio 0
	s_add_i32 s24, s51, s38
	v_lshl_add_u64 v[214:215], v[214:215], 0, s[10:11]
	s_mov_b32 m0, s24
	s_nop 0
	global_load_lds_dwordx4 v[214:215], off
	s_add_i32 m0, s24, 0x2000
	s_add_u32 s22, s22, 0x40080
	v_lshl_add_u64 v[214:215], v[216:217], 0, s[10:11]
	s_addc_u32 s23, s23, 0
	s_add_i32 s24, s52, s38
	global_load_lds_dwordx4 v[214:215], off
	v_lshl_add_u64 v[214:215], s[22:23], 0, v[130:131]
	s_mov_b32 m0, s24
	s_nop 0
	global_load_lds_dwordx4 v[214:215], off
	v_lshl_add_u64 v[214:215], s[22:23], 0, v[132:133]
	s_add_i32 m0, s24, 0x2000
	s_nop 0
	global_load_lds_dwordx4 v[214:215], off
	v_lshl_add_u64 v[214:215], v[218:219], 0, s[10:11]
	s_mov_b32 m0, s42
	s_nop 0
	global_load_lds_dwordx4 v[214:215], off
	v_lshl_add_u64 v[214:215], v[220:221], 0, s[10:11]
	s_mov_b32 m0, s43
	s_nop 0
	global_load_lds_dwordx4 v[214:215], off
	ds_read_b128 v[182:185], v149 offset:49152
	ds_read_b128 v[186:189], v149 offset:50176
	ds_read_b128 v[190:193], v149 offset:51200
	ds_read_b128 v[194:197], v149 offset:52224
	ds_read_b128 v[198:201], v149 offset:53248
	ds_read_b128 v[202:205], v149 offset:54272
	ds_read_b128 v[206:209], v149 offset:55296
	ds_read_b128 v[210:213], v149 offset:56320
	s_waitcnt vmcnt(8)
	s_waitcnt lgkmcnt(0)
	s_barrier
	s_setprio 1
	s_waitcnt lgkmcnt(0)
	v_mfma_f32_16x16x32_bf16 v[62:65], v[150:153], v[182:185], v[62:65]
	v_mfma_f32_16x16x32_bf16 v[58:61], v[158:161], v[182:185], v[58:61]
	v_mfma_f32_16x16x32_bf16 v[50:53], v[150:153], v[190:193], v[50:53]
	v_mfma_f32_16x16x32_bf16 v[42:45], v[158:161], v[190:193], v[42:45]
	v_mfma_f32_16x16x32_bf16 v[34:37], v[150:153], v[198:201], v[34:37]
	v_mfma_f32_16x16x32_bf16 v[26:29], v[158:161], v[198:201], v[26:29]
	v_mfma_f32_16x16x32_bf16 v[18:21], v[150:153], v[206:209], v[18:21]
	v_mfma_f32_16x16x32_bf16 v[10:13], v[158:161], v[206:209], v[10:13]
	v_mfma_f32_16x16x32_bf16 v[62:65], v[154:157], v[186:189], v[62:65]
	v_mfma_f32_16x16x32_bf16 v[58:61], v[162:165], v[186:189], v[58:61]
	v_mfma_f32_16x16x32_bf16 v[50:53], v[154:157], v[194:197], v[50:53]
	v_mfma_f32_16x16x32_bf16 v[42:45], v[162:165], v[194:197], v[42:45]
	v_mfma_f32_16x16x32_bf16 v[34:37], v[154:157], v[202:205], v[34:37]
	v_mfma_f32_16x16x32_bf16 v[26:29], v[162:165], v[202:205], v[26:29]
	v_mfma_f32_16x16x32_bf16 v[18:21], v[154:157], v[210:213], v[18:21]
	v_mfma_f32_16x16x32_bf16 v[10:13], v[162:165], v[210:213], v[10:13]
	s_setprio 0
	s_setprio 1
	v_mfma_f32_16x16x32_bf16 v[54:57], v[166:169], v[182:185], v[54:57]
	v_mfma_f32_16x16x32_bf16 v[46:49], v[174:177], v[182:185], v[46:49]
	v_mfma_f32_16x16x32_bf16 v[38:41], v[166:169], v[190:193], v[38:41]
	v_mfma_f32_16x16x32_bf16 v[30:33], v[174:177], v[190:193], v[30:33]
	v_mfma_f32_16x16x32_bf16 v[22:25], v[166:169], v[198:201], v[22:25]
	v_mfma_f32_16x16x32_bf16 v[14:17], v[174:177], v[198:201], v[14:17]
	v_mfma_f32_16x16x32_bf16 v[6:9], v[166:169], v[206:209], v[6:9]
	v_mfma_f32_16x16x32_bf16 v[2:5], v[174:177], v[206:209], v[2:5]
	v_mfma_f32_16x16x32_bf16 v[54:57], v[170:173], v[186:189], v[54:57]
	v_mfma_f32_16x16x32_bf16 v[46:49], v[178:181], v[186:189], v[46:49]
	v_mfma_f32_16x16x32_bf16 v[38:41], v[170:173], v[194:197], v[38:41]
	v_mfma_f32_16x16x32_bf16 v[30:33], v[178:181], v[194:197], v[30:33]
	v_mfma_f32_16x16x32_bf16 v[22:25], v[170:173], v[202:205], v[22:25]
	v_mfma_f32_16x16x32_bf16 v[14:17], v[178:181], v[202:205], v[14:17]
	v_mfma_f32_16x16x32_bf16 v[6:9], v[170:173], v[210:213], v[6:9]
	s_barrier
	v_mfma_f32_16x16x32_bf16 v[2:5], v[178:181], v[210:213], v[2:5]
	s_setprio 0
	s_add_i32 s50, s50, 2
	s_add_u32 s20, s20, 0x100
	s_addc_u32 s21, s21, 0
	s_cmp_gt_u32 s50, 13
	s_cbranch_scc0 .LBB0_968
	s_add_u32 s20, s48, 0xffffff00
	s_addc_u32 s21, s49, -1
	s_andn2_b64 vcc, exec, s[2:3]
	s_cbranch_vccnz .LBB0_959
	v_mov_b32_e32 v2, 0
	s_mov_b32 s6, s12
	s_mov_b32 s4, s14
	s_mov_b64 s[8:9], s[18:19]
	s_mov_b32 s44, s47
	v_mov_b32_e32 v3, v2
	v_mov_b32_e32 v4, v2
	v_mov_b32_e32 v5, v2
	v_mov_b32_e32 v6, v2
	v_mov_b32_e32 v7, v2
	v_mov_b32_e32 v8, v2
	v_mov_b32_e32 v9, v2
	v_mov_b32_e32 v14, v2
	v_mov_b32_e32 v15, v2
	v_mov_b32_e32 v16, v2
	v_mov_b32_e32 v17, v2
	v_mov_b32_e32 v22, v2
	v_mov_b32_e32 v23, v2
	v_mov_b32_e32 v24, v2
	v_mov_b32_e32 v25, v2
	v_mov_b32_e32 v30, v2
	v_mov_b32_e32 v31, v2
	v_mov_b32_e32 v32, v2
	v_mov_b32_e32 v33, v2
	v_mov_b32_e32 v38, v2
	v_mov_b32_e32 v39, v2
	v_mov_b32_e32 v40, v2
	v_mov_b32_e32 v41, v2
	v_mov_b32_e32 v46, v2
	v_mov_b32_e32 v47, v2
	v_mov_b32_e32 v48, v2
	v_mov_b32_e32 v49, v2
	v_mov_b32_e32 v54, v2
	v_mov_b32_e32 v55, v2
	v_mov_b32_e32 v56, v2
	v_mov_b32_e32 v57, v2
	v_mov_b32_e32 v10, v2
	v_mov_b32_e32 v11, v2
	v_mov_b32_e32 v12, v2
	v_mov_b32_e32 v13, v2
	v_mov_b32_e32 v18, v2
	v_mov_b32_e32 v19, v2
	v_mov_b32_e32 v20, v2
	v_mov_b32_e32 v21, v2
	v_mov_b32_e32 v26, v2
	v_mov_b32_e32 v27, v2
	v_mov_b32_e32 v28, v2
	v_mov_b32_e32 v29, v2
	v_mov_b32_e32 v34, v2
	v_mov_b32_e32 v35, v2
	v_mov_b32_e32 v36, v2
	v_mov_b32_e32 v37, v2
	v_mov_b32_e32 v42, v2
	v_mov_b32_e32 v43, v2
	v_mov_b32_e32 v44, v2
	v_mov_b32_e32 v45, v2
	v_mov_b32_e32 v50, v2
	v_mov_b32_e32 v51, v2
	v_mov_b32_e32 v52, v2
	v_mov_b32_e32 v53, v2
	v_mov_b32_e32 v58, v2
	v_mov_b32_e32 v59, v2
	v_mov_b32_e32 v60, v2
	v_mov_b32_e32 v61, v2
	v_mov_b32_e32 v62, v2
	v_mov_b32_e32 v63, v2
	v_mov_b32_e32 v64, v2
	v_mov_b32_e32 v65, v2
	v_mov_b32_e32 v66, v2
	v_mov_b32_e32 v67, v2
	v_mov_b32_e32 v68, v2
	v_mov_b32_e32 v69, v2
	v_mov_b32_e32 v70, v2
	v_mov_b32_e32 v71, v2
	v_mov_b32_e32 v72, v2
	v_mov_b32_e32 v73, v2
	v_mov_b32_e32 v78, v2
	v_mov_b32_e32 v79, v2
	v_mov_b32_e32 v80, v2
	v_mov_b32_e32 v81, v2
	v_mov_b32_e32 v86, v2
	v_mov_b32_e32 v87, v2
	v_mov_b32_e32 v88, v2
	v_mov_b32_e32 v89, v2
	v_mov_b32_e32 v94, v2
	v_mov_b32_e32 v95, v2
	v_mov_b32_e32 v96, v2
	v_mov_b32_e32 v97, v2
	v_mov_b32_e32 v102, v2
	v_mov_b32_e32 v103, v2
	v_mov_b32_e32 v104, v2
	v_mov_b32_e32 v105, v2
	v_mov_b32_e32 v110, v2
	v_mov_b32_e32 v111, v2
	v_mov_b32_e32 v112, v2
	v_mov_b32_e32 v113, v2
	v_mov_b32_e32 v118, v2
	v_mov_b32_e32 v119, v2
	v_mov_b32_e32 v120, v2
	v_mov_b32_e32 v121, v2
	v_mov_b32_e32 v74, v2
	v_mov_b32_e32 v75, v2
	v_mov_b32_e32 v76, v2
	v_mov_b32_e32 v77, v2
	v_mov_b32_e32 v82, v2
	v_mov_b32_e32 v83, v2
	v_mov_b32_e32 v84, v2
	v_mov_b32_e32 v85, v2
	v_mov_b32_e32 v90, v2
	v_mov_b32_e32 v91, v2
	v_mov_b32_e32 v92, v2
	v_mov_b32_e32 v93, v2
	v_mov_b32_e32 v98, v2
	v_mov_b32_e32 v99, v2
	v_mov_b32_e32 v100, v2
	v_mov_b32_e32 v101, v2
	v_mov_b32_e32 v106, v2
	v_mov_b32_e32 v107, v2
	v_mov_b32_e32 v108, v2
	v_mov_b32_e32 v109, v2
	v_mov_b32_e32 v114, v2
	v_mov_b32_e32 v115, v2
	v_mov_b32_e32 v116, v2
	v_mov_b32_e32 v117, v2
	v_mov_b32_e32 v122, v2
	v_mov_b32_e32 v123, v2
	v_mov_b32_e32 v124, v2
	v_mov_b32_e32 v125, v2
	v_mov_b32_e32 v126, v2
	v_mov_b32_e32 v127, v2
	v_mov_b32_e32 v128, v2
	v_mov_b32_e32 v129, v2
	s_andn2_b64 vcc, exec, s[0:1]
	s_cbranch_vccnz .LBB0_960
